# speedup vs baseline: 1.0063x; 1.0063x over previous
; #define MFMA16(a, b, c) __builtin_amdgcn_mfma_f32_16x16x32_bf16((a), (b), (c), 0, 0, 0)
;   __device__ __forceinline__ float* r() const { return (float*)(b + L::o_r); }
; template <bool FOX, int G>
; __device__ __forceinline__ void p3_attn(const Ptrs<G>& w, int seq, int h, int qb, bfu* sm, int kslot) {
;     ...
;     if (s0 <= qrow0) {
;       f32x4 S[4][2];
; #pragma unroll
;       for (int i = 0; i < 4; ++i) {
;         bf16x8 ka0 = *(const bf16x8*)(Ks + (16 * i + c15) * 72 + 8 * g);
;         bf16x8 ka1 = *(const bf16x8*)(Ks + (16 * i + c15) * 72 + 32 + 8 * g);
; #pragma unroll
;         for (int j = 0; j < 2; ++j) {
;           f32x4 z = (f32x4){0.f, 0.f, 0.f, 0.f};
;           z = MFMA16(ka0, Qf[j][0], z);
;           S[i][j] = MFMA16(ka1, Qf[j][1], z);
;         }
;       }
;       if (FOX) {
;         float4 Fs[4];
; #pragma unroll
;         for (int i = 0; i < 4; ++i) Fs[i] = *(const float4*)(Fh + s0 + 16 * i + 4 * g);
; #pragma unroll
;         for (int j = 0; j < 2; ++j) {
;           const int t = qrow0 + 16 * j + c15;
;           float mx = -1e30f;
; #pragma unroll
;           for (int i = 0; i < 4; ++i) {
;             const float fs[4] = {Fs[i].x, Fs[i].y, Fs[i].z, Fs[i].w};
; #pragma unroll
;             for (int r = 0; r < 4; ++r) {
;               const int s = s0 + 16 * i + 4 * g + r;
;               float z = S[i][j][r] + (Ft[j] - fs[r]);
;               z = (s <= t) ? z : -1e30f;
;               S[i][j][r] = z; mx = fmaxf(mx, z);
;             }
;           }
;           mx = fmaxf(mx, __shfl_xor(mx, 16)); mx = fmaxf(mx, __shfl_xor(mx, 32));
;           const float mnew = fmaxf(mrun[j], mx);
;           const float alpha = __expf(mrun[j] - mnew);
;           mrun[j] = mnew;
;           float ps = 0.f;
; #pragma unroll
;           for (int i = 0; i < 4; ++i)
; #pragma unroll
;             for (int r = 0; r < 4; ++r) { float p = __expf(S[i][j][r] - mnew); S[i][j][r] = p; ps += p; }
;           ps += __shfl_xor(ps, 16); ps += __shfl_xor(ps, 32);
;           lsum[j] = lsum[j] * alpha + ps;
; #pragma unroll
;           for (int dt = 0; dt < 4; ++dt) O[dt][j] = O[dt][j] * alpha;
;         }
.LBB0_326:
	v_cmp_le_i32_e32 vcc, s2, v116
	s_and_saveexec_b64 s[20:21], vcc
	s_cbranch_execz .LBB0_319
	s_add_i32 s0, s2, 63
	v_cmp_le_i32_e32 vcc, s0, v116
	s_cbranch_vccz .Lfox_masked
	ds_read_b128 v[64:67], v139
	ds_read_b128 v[80:83], v139 offset:64
	v_lshlrev_b32_e32 v108, 2, v132
	v_add_u32_e32 v142, s12, v132
	v_add_u32_e32 v143, 64, v142
	s_waitcnt lgkmcnt(1)
	v_mfma_f32_16x16x32_bf16 v[68:71], v[64:67], v[12:15], 0
	v_add_u32_e32 v145, 0x42, v142
	v_add_u32_e32 v147, 0x43, v142
	s_waitcnt lgkmcnt(0)
	v_mfma_f32_16x16x32_bf16 v[100:103], v[80:83], v[16:19], v[68:71]
	s_nop 2
	s_nop 0
	ds_read_b128 v[68:71], v139 offset:2304
	ds_read_b128 v[84:87], v139 offset:2368
	ds_read_b128 v[72:75], v139 offset:4608
	ds_read_b128 v[148:151], v139 offset:4672
	ds_read_b128 v[88:91], v139 offset:6912
	global_load_dwordx4 v[76:79], v108, s[22:23]
	v_mfma_f32_16x16x32_bf16 v[64:67], v[64:67], v[20:23], 0
	ds_read_b128 v[92:95], v139 offset:6976
	v_add_u32_e32 v144, 0x50, v142
	v_add_u32_e32 v159, 0x51, v142
	s_waitcnt lgkmcnt(3)
	v_mfma_f32_16x16x32_bf16 v[164:167], v[72:75], v[12:15], 0
	v_add_u32_e32 v161, 0x52, v142
	v_add_u32_e32 v163, 0x53, v142
	v_add_u32_e32 v169, 0x62, v142
	v_mfma_f32_16x16x32_bf16 v[170:173], v[72:75], v[20:23], 0
	global_load_dwordx4 v[72:75], v108, s[22:23] offset:64
	v_add_u32_e32 v198, 0x63, v142
	v_mfma_f32_16x16x32_bf16 v[96:99], v[68:71], v[12:15], 0
	s_mov_b32 s2, 0xf149f2ca
	v_add_u32_e32 v200, 0x73, v142
	s_waitcnt vmcnt(1)
	v_sub_f32_e32 v157, v121, v77
	v_mfma_f32_16x16x32_bf16 v[104:107], v[68:71], v[20:23], 0
	global_load_dwordx4 v[68:71], v108, s[22:23] offset:128
	v_add_f32_e32 v101, v101, v157
	v_mfma_f32_16x16x32_bf16 v[80:83], v[80:83], v[24:27], v[64:67]
	v_sub_f32_e32 v146, v121, v76
	v_add_f32_e32 v100, v100, v146
	global_load_dwordx4 v[64:67], v108, s[22:23] offset:192
	v_mfma_f32_16x16x32_bf16 v[108:111], v[84:87], v[16:19], v[96:99]
	v_sub_f32_e32 v76, v120, v76
	s_nop 0
	s_nop 1
	v_add_f32_e32 v76, v80, v76
	v_mfma_f32_16x16x32_bf16 v[84:87], v[84:87], v[24:27], v[104:107]
	v_sub_f32_e32 v77, v120, v77
	v_add_f32_e32 v77, v81, v77
	s_waitcnt vmcnt(0)
	v_sub_f32_e32 v146, v121, v64
	s_waitcnt lgkmcnt(2)
	v_mfma_f32_16x16x32_bf16 v[104:107], v[148:151], v[16:19], v[164:167]
	v_sub_f32_e32 v64, v120, v64
	s_nop 1
	v_sub_f32_e32 v164, v121, v78
	v_sub_f32_e32 v166, v121, v79
	v_add_f32_e32 v102, v102, v164
	s_waitcnt lgkmcnt(1)
	v_mfma_f32_16x16x32_bf16 v[184:187], v[88:91], v[12:15], 0
	v_add_f32_e32 v103, v103, v166
	v_mfma_f32_16x16x32_bf16 v[96:99], v[148:151], v[24:27], v[170:173]
	v_add_u32_e32 v165, 0x60, v142
	v_sub_f32_e32 v170, v121, v72
	v_sub_f32_e32 v171, v121, v73
	v_add_f32_e32 v108, v108, v170
	v_sub_f32_e32 v172, v121, v74
	v_add_f32_e32 v109, v109, v171
	v_sub_f32_e32 v173, v121, v75
	v_add_f32_e32 v110, v110, v172
	s_waitcnt lgkmcnt(0)
	v_mfma_f32_16x16x32_bf16 v[148:151], v[92:95], v[16:19], v[184:187]
	v_add_f32_e32 v111, v111, v173
	v_sub_f32_e32 v184, v121, v68
	v_add_u32_e32 v167, 0x61, v142
	v_sub_f32_e32 v185, v121, v69
	v_add_f32_e32 v104, v104, v184
	v_sub_f32_e32 v186, v121, v70
	v_add_f32_e32 v105, v105, v185
	v_sub_f32_e32 v187, v121, v71
	v_add_f32_e32 v106, v106, v186
	v_add_f32_e32 v107, v107, v187
	v_add_u32_e32 v184, 0x70, v142
	v_max3_f32 v144, v100, s2, v101
	v_add_f32_e32 v146, v148, v146
	v_max3_f32 v144, v144, v102, v103
	v_add_u32_e32 v186, 0x71, v142
	v_mov_b32_e32 v185, v146
	v_sub_f32_e32 v146, v121, v65
	v_max3_f32 v144, v144, v108, v109
	v_add_f32_e32 v146, v149, v146
	v_max3_f32 v144, v144, v110, v111
	v_add_u32_e32 v187, 0x72, v142
	v_mov_b32_e32 v149, v146
	v_sub_f32_e32 v146, v121, v66
	v_max3_f32 v144, v144, v104, v105
	v_add_f32_e32 v146, v150, v146
	v_sub_f32_e32 v142, v121, v67
	v_max3_f32 v144, v144, v106, v107
	v_mov_b32_e32 v199, v146
	v_add_f32_e32 v142, v151, v142
	v_max3_f32 v144, v144, v185, v149
	v_sub_f32_e32 v72, v120, v72
	v_mov_b32_e32 v151, v142
	v_max3_f32 v142, v144, v199, v151
	v_mfma_f32_16x16x32_bf16 v[88:91], v[88:91], v[20:23], 0
	v_add_f32_e32 v72, v84, v72
	v_sub_f32_e32 v73, v120, v73
	ds_bpermute_b32 v144, v119, v142
	v_add_f32_e32 v73, v85, v73
	v_sub_f32_e32 v74, v120, v74
	v_add_f32_e32 v74, v86, v74
	v_sub_f32_e32 v75, v120, v75
	v_add_f32_e32 v75, v87, v75
	v_sub_f32_e32 v68, v120, v68
	v_mfma_f32_16x16x32_bf16 v[170:173], v[92:95], v[24:27], v[88:91]
	v_add_f32_e32 v68, v96, v68
	v_sub_f32_e32 v69, v120, v69
	v_sub_f32_e32 v78, v120, v78
	v_add_f32_e32 v69, v97, v69
	v_sub_f32_e32 v70, v120, v70
	s_waitcnt lgkmcnt(0)
	v_max_f32_e32 v144, v144, v144
	v_add_f32_e32 v78, v82, v78
	v_sub_f32_e32 v79, v120, v79
	v_add_f32_e32 v70, v98, v70
	v_sub_f32_e32 v71, v120, v71
	v_max_f32_e32 v142, v142, v144
	v_add_f32_e32 v79, v83, v79
	v_add_f32_e32 v71, v99, v71
	ds_bpermute_b32 v144, v133, v142
	v_max3_f32 v80, v76, s2, v77
	v_add_f32_e32 v64, v170, v64
	v_max3_f32 v80, v80, v78, v79
	v_max3_f32 v80, v80, v72, v73
	v_mov_b32_e32 v81, v64
	v_sub_f32_e32 v64, v120, v65
	v_add_f32_e32 v64, v171, v64
	v_sub_f32_e32 v65, v120, v66
	v_max3_f32 v80, v80, v74, v75
	v_mov_b32_e32 v82, v64
	v_add_f32_e32 v65, v172, v65
	v_max3_f32 v80, v80, v68, v69
	s_waitcnt lgkmcnt(0)
	v_max3_f32 v157, v141, v142, v144
	v_mov_b32_e32 v84, v65
	v_sub_f32_e32 v65, v120, v67
	v_max3_f32 v80, v80, v70, v71
	v_add_f32_e32 v65, v173, v65
	v_sub_f32_e32 v89, v100, v157
	v_max3_f32 v64, v80, v81, v82
	v_mov_b32_e32 v85, v65
	v_mul_f32_e32 v89, 0x3fb8aa3b, v89
	v_max3_f32 v64, v64, v84, v85
	v_exp_f32_e32 v164, v89
	v_sub_f32_e32 v89, v101, v157
	ds_bpermute_b32 v65, v119, v64
	v_mul_f32_e32 v89, 0x3fb8aa3b, v89
	v_exp_f32_e32 v166, v89
	v_sub_f32_e32 v89, v102, v157
	v_mul_f32_e32 v89, 0x3fb8aa3b, v89
	v_exp_f32_e32 v142, v89
	v_sub_f32_e32 v89, v103, v157
	v_mul_f32_e32 v89, 0x3fb8aa3b, v89
	s_waitcnt lgkmcnt(0)
; template <bool FOX, int G>
; __device__ __forceinline__ void p3_attn(const Ptrs<G>& w, int seq, int h, int qb, bfu* sm, int kslot) {
;     ...
;           const float mnew = fmaxf(mrun[j], mx);
;           const float alpha = __expf(mrun[j] - mnew);
;           mrun[j] = mnew;
;           float ps = 0.f;
; #pragma unroll
;           for (int i = 0; i < 4; ++i)
; #pragma unroll
;             for (int r = 0; r < 4; ++r) { float p = __expf(S[i][j][r] - mnew); S[i][j][r] = p; ps += p; }
;           ps += __shfl_xor(ps, 16); ps += __shfl_xor(ps, 32);
;           lsum[j] = lsum[j] * alpha + ps;
; #pragma unroll
;           for (int dt = 0; dt < 4; ++dt) O[dt][j] = O[dt][j] * alpha;
;         }
;       } else {
; #pragma unroll
;         for (int j = 0; j < 2; ++j) {
;           const int t = qrow0 + 16 * j + c15;
;           float LR[4][4];
; #pragma unroll
;           for (int i = 0; i < 4; ++i)
; #pragma unroll
;             for (int r = 0; r < 4; ++r) {
;               const int s = s0 + 16 * i + 4 * g + r;
;               const float z = S[i][j][r];
;               const float lp = __logf(1.f + __expf(-fabsf(z)));
;               const bool valid = s < t;
;               S[i][j][r] = fminf(z, 0.f) - lp;
;               LR[i][r] = valid ? (fminf(-z, 0.f) - lp) : 0.f;
;             }
;           float running = Rrun[j];
; #pragma unroll
;           for (int i = 3; i >= 0; --i) {
;             const float c = (LR[i][0] + LR[i][1]) + (LR[i][2] + LR[i][3]);
;             const float v0 = __shfl(c, c15), v1 = __shfl(c, c15 + 16), v2 = __shfl(c, c15 + 32), v3 = __shfl(c, c15 + 48);
;             const float Eg = (g < 1 ? v1 : 0.f) + (g < 2 ? v2 : 0.f) + (g < 3 ? v3 : 0.f);
;             const float b3 = running + Eg, b2 = b3 + LR[i][3], b1 = b2 + LR[i][2], b0 = b1 + LR[i][1];
;             const int sb = s0 + 16 * i + 4 * g;
;             S[i][j][0] = (sb + 0 < t) ? __expf(S[i][j][0] + b0) : 0.f;
;             S[i][j][1] = (sb + 1 < t) ? __expf(S[i][j][1] + b1) : 0.f;
;             S[i][j][2] = (sb + 2 < t) ? __expf(S[i][j][2] + b2) : 0.f;
;             S[i][j][3] = (sb + 3 < t) ? __expf(S[i][j][3] + b3) : 0.f;
;             running += (v0 + v1) + (v2 + v3);
;           }
;           Rrun[j] = running;
;         }
;       }
; #pragma unroll
;       for (int sb = 0; sb < 2; ++sb) {
;         bf16x8 Pb[2];
; #pragma unroll
;         for (int j = 0; j < 2; ++j) {
	v_max_f32_e32 v65, v65, v65
	v_exp_f32_e32 v144, v89
	v_sub_f32_e32 v89, v108, v157
	v_max_f32_e32 v64, v64, v65
	v_mul_f32_e32 v89, 0x3fb8aa3b, v89
	ds_bpermute_b32 v65, v133, v64
	v_exp_f32_e32 v146, v89
	v_sub_f32_e32 v89, v109, v157
	v_mul_f32_e32 v89, 0x3fb8aa3b, v89
	v_exp_f32_e32 v148, v89
	v_sub_f32_e32 v89, v110, v157
	v_mul_f32_e32 v89, 0x3fb8aa3b, v89
	v_exp_f32_e32 v150, v89
	v_sub_f32_e32 v89, v111, v157
	s_waitcnt lgkmcnt(0)
	v_max3_f32 v67, v140, v64, v65
	v_mul_f32_e32 v89, 0x3fb8aa3b, v89
	v_sub_f32_e32 v64, v140, v67
	v_exp_f32_e32 v108, v89
	v_sub_f32_e32 v89, v104, v157
	v_mul_f32_e32 v66, 0x3fb8aa3b, v64
	v_sub_f32_e32 v64, v76, v67
	v_mul_f32_e32 v89, 0x3fb8aa3b, v89
	v_mul_f32_e32 v64, 0x3fb8aa3b, v64
	v_exp_f32_e32 v110, v89
	v_sub_f32_e32 v89, v105, v157
	v_exp_f32_e32 v165, v64
	v_sub_f32_e32 v64, v77, v67
	v_mul_f32_e32 v89, 0x3fb8aa3b, v89
	v_mul_f32_e32 v64, 0x3fb8aa3b, v64
	v_exp_f32_e32 v92, v89
	v_sub_f32_e32 v89, v106, v157
	v_exp_f32_e32 v167, v64
	v_sub_f32_e32 v64, v78, v67
	v_mul_f32_e32 v89, 0x3fb8aa3b, v89
	v_mul_f32_e32 v64, 0x3fb8aa3b, v64
	v_exp_f32_e32 v94, v89
	v_sub_f32_e32 v89, v107, v157
	v_exp_f32_e32 v143, v64
	v_sub_f32_e32 v64, v79, v67
	v_mul_f32_e32 v89, 0x3fb8aa3b, v89
	v_mul_f32_e32 v64, 0x3fb8aa3b, v64
	v_exp_f32_e32 v100, v89
	v_sub_f32_e32 v89, v185, v157
	v_exp_f32_e32 v145, v64
	v_sub_f32_e32 v64, v72, v67
	v_mul_f32_e32 v89, 0x3fb8aa3b, v89
	v_mul_f32_e32 v64, 0x3fb8aa3b, v64
	v_exp_f32_e32 v102, v89
	v_sub_f32_e32 v89, v149, v157
	v_exp_f32_e32 v147, v64
	v_sub_f32_e32 v64, v73, v67
	v_mul_f32_e32 v89, 0x3fb8aa3b, v89
	v_mul_f32_e32 v64, 0x3fb8aa3b, v64
	v_exp_f32_e32 v104, v89
	v_sub_f32_e32 v89, v199, v157
	v_exp_f32_e32 v149, v64
	v_sub_f32_e32 v64, v74, v67
	v_mul_f32_e32 v89, 0x3fb8aa3b, v89
	v_mul_f32_e32 v64, 0x3fb8aa3b, v64
	v_exp_f32_e32 v106, v89
	v_sub_f32_e32 v89, v151, v157
	v_exp_f32_e32 v151, v64
	v_sub_f32_e32 v64, v75, v67
	v_mul_f32_e32 v64, 0x3fb8aa3b, v64
	v_exp_f32_e32 v109, v64
	v_sub_f32_e32 v64, v68, v67
	v_sub_f32_e32 v68, v69, v67
	v_mul_f32_e32 v68, 0x3fb8aa3b, v68
	v_exp_f32_e32 v93, v68
	v_sub_f32_e32 v68, v70, v67
	v_mul_f32_e32 v68, 0x3fb8aa3b, v68
	v_exp_f32_e32 v95, v68
	v_sub_f32_e32 v68, v71, v67
	v_sub_f32_e32 v88, v141, v157
	v_mul_f32_e32 v68, 0x3fb8aa3b, v68
	v_mul_f32_e32 v88, 0x3fb8aa3b, v88
	v_exp_f32_e32 v101, v68
	v_sub_f32_e32 v68, v81, v67
	v_exp_f32_e32 v88, v88
	v_mul_f32_e32 v68, 0x3fb8aa3b, v68
	v_add_u32_e32 v87, 0x2000, v168
	v_exp_f32_e32 v103, v68
	ds_read2_b64 v[68:71], v87 offset0:128 offset1:132
	v_mul_f32_e32 v89, 0x3fb8aa3b, v89
	v_exp_f32_e32 v90, v89
	v_pk_mul_f32 v[62:63], v[62:63], v[88:89] op_sel_hi:[1,0]
	v_pk_mul_f32 v[60:61], v[60:61], v[88:89] op_sel_hi:[1,0]
	v_pk_mul_f32 v[58:59], v[58:59], v[88:89] op_sel_hi:[1,0]
	v_pk_mul_f32 v[56:57], v[56:57], v[88:89] op_sel_hi:[1,0]
	v_pk_mul_f32 v[54:55], v[54:55], v[88:89] op_sel_hi:[1,0]
	v_pk_mul_f32 v[52:53], v[52:53], v[88:89] op_sel_hi:[1,0]
	v_pk_mul_f32 v[50:51], v[50:51], v[88:89] op_sel_hi:[1,0]
	v_pk_mul_f32 v[48:49], v[48:49], v[88:89] op_sel_hi:[1,0]
	v_exp_f32_e32 v89, v66
	v_add_u32_e32 v96, 0x2800, v168
	v_sub_f32_e32 v66, v82, v67
	ds_read2_b64 v[80:83], v96 offset0:160 offset1:164
	v_mul_f32_e32 v86, 0x3fb8aa3b, v66
	v_mov_b32_e32 v66, v89
	v_pk_mul_f32 v[30:31], v[30:31], v[66:67] op_sel_hi:[1,0]
	v_pk_mul_f32 v[28:29], v[28:29], v[66:67] op_sel_hi:[1,0]
	v_cvt_pk_bf16_f32 v72, v164, v166
	v_cvt_pk_bf16_f32 v73, v142, v144
	v_cvt_pk_bf16_f32 v74, v146, v148
	v_cvt_pk_bf16_f32 v75, v150, v108
	v_cvt_pk_bf16_f32 v76, v165, v167
	v_cvt_pk_bf16_f32 v77, v143, v145
	v_cvt_pk_bf16_f32 v78, v147, v149
	v_cvt_pk_bf16_f32 v79, v151, v109
	v_exp_f32_e32 v105, v86
	v_add_u32_e32 v86, 0x3000, v168
	s_waitcnt lgkmcnt(1)
	v_mfma_f32_16x16x32_bf16 v[60:63], v[68:71], v[72:75], v[60:63]
	v_mul_f32_e64 v10, v10, v66
	v_mul_f32_e64 v11, v11, v66
	v_pk_mul_f32 v[8:9], v[8:9], v[66:67] op_sel_hi:[1,0]
	v_add_u32_e32 v97, 0x3800, v168
	v_mfma_f32_16x16x32_bf16 v[28:31], v[68:71], v[76:79], v[28:31]
	ds_read2_b64 v[68:71], v86 offset0:192 offset1:196
	v_mul_f32_e32 v64, 0x3fb8aa3b, v64
	v_exp_f32_e32 v111, v64
	s_waitcnt lgkmcnt(1)
	v_mfma_f32_16x16x32_bf16 v[56:59], v[80:83], v[72:75], v[56:59]
	v_add_f32_e64 v64, v164, 0
	v_add_f32_e64 v65, v165, 0
	v_pk_mul_f32 v[6:7], v[6:7], v[66:67] op_sel_hi:[1,0]
	v_pk_add_f32 v[64:65], v[166:167], v[64:65]
	v_mfma_f32_16x16x32_bf16 v[8:11], v[80:83], v[76:79], v[8:11]
	ds_read2_b64 v[80:83], v97 offset0:224 offset1:228
	v_pk_mul_f32 v[4:5], v[4:5], v[66:67] op_sel_hi:[1,0]
	v_pk_add_f32 v[64:65], v[142:143], v[64:65]
	s_waitcnt lgkmcnt(1)
	v_mfma_f32_16x16x32_bf16 v[52:55], v[68:71], v[72:75], v[52:55]
	v_add_f32_e64 v64, v144, v64
	v_add_f32_e64 v65, v145, v65
	v_sub_f32_e32 v84, v84, v67
	v_pk_add_f32 v[64:65], v[146:147], v[64:65]
	v_mfma_f32_16x16x32_bf16 v[4:7], v[68:71], v[76:79], v[4:7]
	v_sub_f32_e32 v68, v85, v67
	v_mul_f32_e32 v68, 0x3fb8aa3b, v68
	v_exp_f32_e32 v91, v68
	ds_read2_b64 v[68:71], v87 offset0:136 offset1:140
	v_pk_add_f32 v[64:65], v[148:149], v[64:65]
	v_pk_mul_f32 v[2:3], v[2:3], v[66:67] op_sel_hi:[1,0]
	v_pk_add_f32 v[64:65], v[150:151], v[64:65]
	v_pk_mul_f32 v[0:1], v[0:1], v[66:67] op_sel_hi:[1,0]
	v_mul_f32_e32 v84, 0x3fb8aa3b, v84
	s_waitcnt lgkmcnt(1)
; #define MFMA16(a, b, c) __builtin_amdgcn_mfma_f32_16x16x32_bf16((a), (b), (c), 0, 0, 0)
;   __device__ __forceinline__ float* r() const { return (float*)(b + L::o_r); }
; template <bool FOX, int G>
; __device__ __forceinline__ void p3_attn(const Ptrs<G>& w, int seq, int h, int qb, bfu* sm, int kslot) {
;     ...
;       f32x4 S[4][2];
; #pragma unroll
;       for (int i = 0; i < 4; ++i) {
;         bf16x8 ka0 = *(const bf16x8*)(Ks + (16 * i + c15) * 72 + 8 * g);
;         bf16x8 ka1 = *(const bf16x8*)(Ks + (16 * i + c15) * 72 + 32 + 8 * g);
; #pragma unroll
;         for (int j = 0; j < 2; ++j) {
;           f32x4 z = (f32x4){0.f, 0.f, 0.f, 0.f};
;           z = MFMA16(ka0, Qf[j][0], z);
;           S[i][j] = MFMA16(ka1, Qf[j][1], z);
;         }
;       }
;       if (FOX) {
;         float4 Fs[4];
; #pragma unroll
;         for (int i = 0; i < 4; ++i) Fs[i] = *(const float4*)(Fh + s0 + 16 * i + 4 * g);
; #pragma unroll
;         for (int j = 0; j < 2; ++j) {
;           const int t = qrow0 + 16 * j + c15;
;           float mx = -1e30f;
; #pragma unroll
;           for (int i = 0; i < 4; ++i) {
;             const float fs[4] = {Fs[i].x, Fs[i].y, Fs[i].z, Fs[i].w};
; #pragma unroll
;             for (int r = 0; r < 4; ++r) {
;               const int s = s0 + 16 * i + 4 * g + r;
;               float z = S[i][j][r] + (Ft[j] - fs[r]);
;               z = (s <= t) ? z : -1e30f;
;               S[i][j][r] = z; mx = fmaxf(mx, z);
;     ...
;       for (int sb = 0; sb < 2; ++sb) {
;         bf16x8 Pb[2];
; #pragma unroll
;         for (int j = 0; j < 2; ++j) {
;           unsigned u0 = pack2(S[2 * sb][j][0], S[2 * sb][j][1]), u1 = pack2(S[2 * sb][j][2], S[2 * sb][j][3]);
;           unsigned u2 = pack2(S[2 * sb + 1][j][0], S[2 * sb + 1][j][1]), u3 = pack2(S[2 * sb + 1][j][2], S[2 * sb + 1][j][3]);
;           uint4 t4 = make_uint4(u0, u1, u2, u3);
;           Pb[j] = *(bf16x8*)&t4;
;         }
; #pragma unroll
;         for (int dt = 0; dt < 4; ++dt) {
;           uint2 lo = *(const uint2*)(Vs + (16 * dt + c15) * 72 + 32 * sb + 4 * g);
;           uint2 hi = *(const uint2*)(Vs + (16 * dt + c15) * 72 + 32 * sb + 16 + 4 * g);
;           uint4 t4 = make_uint4(lo.x, lo.y, hi.x, hi.y);
;           bf16x8 va = *(bf16x8*)&t4;
; #pragma unroll
;           for (int j = 0; j < 2; ++j) O[dt][j] = MFMA16(va, Pb[j], O[dt][j]);
	v_mfma_f32_16x16x32_bf16 v[48:51], v[80:83], v[72:75], v[48:51]
	v_add_f32_e64 v64, v108, v64
	v_add_f32_e64 v65, v109, v65
	v_exp_f32_e32 v107, v84
	v_pk_add_f32 v[64:65], v[110:111], v[64:65]
	v_mfma_f32_16x16x32_bf16 v[0:3], v[80:83], v[76:79], v[0:3]
	ds_read2_b64 v[80:83], v96 offset0:168 offset1:172
	v_pk_add_f32 v[64:65], v[92:93], v[64:65]
	v_cvt_pk_bf16_f32 v72, v110, v92
	v_pk_add_f32 v[64:65], v[94:95], v[64:65]
	v_cvt_pk_bf16_f32 v73, v94, v100
	v_pk_add_f32 v[64:65], v[100:101], v[64:65]
	v_cvt_pk_bf16_f32 v74, v102, v104
	v_cvt_pk_bf16_f32 v75, v106, v90
	v_cvt_pk_bf16_f32 v76, v111, v93
	v_cvt_pk_bf16_f32 v77, v95, v101
	v_cvt_pk_bf16_f32 v78, v103, v105
	v_cvt_pk_bf16_f32 v79, v107, v91
	v_pk_add_f32 v[64:65], v[102:103], v[64:65]
	s_waitcnt lgkmcnt(1)
	v_mfma_f32_16x16x32_bf16 v[60:63], v[68:71], v[72:75], v[60:63]
	v_add_f32_e64 v64, v104, v64
	v_add_f32_e64 v65, v105, v65
	v_mov_b32_e32 v140, v67
	v_pk_add_f32 v[64:65], v[106:107], v[64:65]
	v_mfma_f32_16x16x32_bf16 v[28:31], v[68:71], v[76:79], v[28:31]
	ds_read2_b64 v[68:71], v86 offset0:200 offset1:204
	v_pk_add_f32 v[64:65], v[90:91], v[64:65]
	ds_bpermute_b32 v84, v119, v64
	s_waitcnt lgkmcnt(2)
	v_mfma_f32_16x16x32_bf16 v[56:59], v[80:83], v[72:75], v[56:59]
	ds_bpermute_b32 v85, v119, v65
	v_mov_b32_e32 v141, v157
	s_waitcnt lgkmcnt(0)
	v_pk_add_f32 v[64:65], v[64:65], v[84:85]
	v_mfma_f32_16x16x32_bf16 v[8:11], v[80:83], v[76:79], v[8:11]
	ds_read2_b64 v[80:83], v97 offset0:232 offset1:236
	v_mfma_f32_16x16x32_bf16 v[52:55], v[68:71], v[72:75], v[52:55]
	v_mfma_f32_16x16x32_bf16 v[4:7], v[68:71], v[76:79], v[4:7]
	ds_bpermute_b32 v68, v133, v64
	ds_bpermute_b32 v69, v133, v65
	s_waitcnt lgkmcnt(0)
	v_pk_add_f32 v[64:65], v[64:65], v[68:69]
	v_mfma_f32_16x16x32_bf16 v[48:51], v[80:83], v[72:75], v[48:51]
	v_fma_f32 v128, v128, v88, v64
	v_fma_f32 v129, v129, v89, v65
	v_mfma_f32_16x16x32_bf16 v[0:3], v[80:83], v[76:79], v[0:3]
	s_branch .LBB0_319
.Lfox_masked:
	ds_read_b128 v[64:67], v139
	ds_read_b128 v[80:83], v139 offset:64
	v_lshlrev_b32_e32 v108, 2, v132
	v_add_u32_e32 v142, s12, v132
	v_add_u32_e32 v143, 64, v142
	s_waitcnt lgkmcnt(1)
	v_mfma_f32_16x16x32_bf16 v[68:71], v[64:67], v[12:15], 0
	v_add_u32_e32 v145, 0x42, v142
	v_cmp_lt_i32_e64 s[0:1], v143, v118
	v_add_u32_e32 v147, 0x43, v142
	s_waitcnt lgkmcnt(0)
	v_mfma_f32_16x16x32_bf16 v[100:103], v[80:83], v[16:19], v[68:71]
	s_nop 2
	ds_read_b128 v[68:71], v139 offset:2304
	ds_read_b128 v[84:87], v139 offset:2368
	ds_read_b128 v[72:75], v139 offset:4608
	ds_read_b128 v[148:151], v139 offset:4672
	ds_read_b128 v[88:91], v139 offset:6912
	global_load_dwordx4 v[76:79], v108, s[22:23]
	v_mfma_f32_16x16x32_bf16 v[64:67], v[64:67], v[20:23], 0
	ds_read_b128 v[92:95], v139 offset:6976
	v_add_u32_e32 v144, 0x50, v142
	v_add_u32_e32 v159, 0x51, v142
	s_waitcnt lgkmcnt(3)
	v_mfma_f32_16x16x32_bf16 v[164:167], v[72:75], v[12:15], 0
	v_add_u32_e32 v161, 0x52, v142
	v_add_u32_e32 v163, 0x53, v142
	v_add_u32_e32 v169, 0x62, v142
	v_mfma_f32_16x16x32_bf16 v[170:173], v[72:75], v[20:23], 0
	global_load_dwordx4 v[72:75], v108, s[22:23] offset:64
	v_add_u32_e32 v198, 0x63, v142
	v_cmp_gt_i32_e32 vcc, v143, v118
	v_mfma_f32_16x16x32_bf16 v[96:99], v[68:71], v[12:15], 0
	s_mov_b32 s2, 0xf149f2ca
	v_add_u32_e32 v200, 0x73, v142
	s_waitcnt vmcnt(1)
	v_sub_f32_e32 v157, v121, v77
	v_mfma_f32_16x16x32_bf16 v[104:107], v[68:71], v[20:23], 0
	global_load_dwordx4 v[68:71], v108, s[22:23] offset:128
	v_add_f32_e32 v101, v101, v157
	v_cndmask_b32_e64 v101, v196, v101, s[0:1]
	v_mfma_f32_16x16x32_bf16 v[80:83], v[80:83], v[24:27], v[64:67]
	v_cmp_le_i32_e64 s[0:1], v145, v118
	v_sub_f32_e32 v146, v121, v76
	v_add_f32_e32 v100, v100, v146
	global_load_dwordx4 v[64:67], v108, s[22:23] offset:192
	v_mfma_f32_16x16x32_bf16 v[108:111], v[84:87], v[16:19], v[96:99]
	v_cndmask_b32_e32 v100, v100, v196, vcc
	v_sub_f32_e32 v76, v120, v76
	s_nop 0
	v_add_f32_e32 v76, v80, v76
	v_mfma_f32_16x16x32_bf16 v[84:87], v[84:87], v[24:27], v[104:107]
	v_sub_f32_e32 v77, v120, v77
	v_add_f32_e32 v77, v81, v77
	s_waitcnt vmcnt(0)
	v_sub_f32_e32 v146, v121, v64
	s_waitcnt lgkmcnt(2)
	v_mfma_f32_16x16x32_bf16 v[104:107], v[148:151], v[16:19], v[164:167]
	v_sub_f32_e32 v64, v120, v64
	s_nop 1
	v_sub_f32_e32 v164, v121, v78
	v_sub_f32_e32 v166, v121, v79
	v_add_f32_e32 v102, v102, v164
	s_waitcnt lgkmcnt(1)
	v_mfma_f32_16x16x32_bf16 v[184:187], v[88:91], v[12:15], 0
	v_add_f32_e32 v103, v103, v166
	v_cndmask_b32_e64 v102, v196, v102, s[0:1]
	v_cmp_le_i32_e64 s[0:1], v147, v118
	v_mfma_f32_16x16x32_bf16 v[96:99], v[148:151], v[24:27], v[170:173]
	v_add_u32_e32 v165, 0x60, v142
	v_cndmask_b32_e64 v103, v196, v103, s[0:1]
	v_cmp_le_i32_e64 s[0:1], v144, v118
	v_sub_f32_e32 v170, v121, v72
	v_sub_f32_e32 v171, v121, v73
	v_add_f32_e32 v108, v108, v170
	v_sub_f32_e32 v172, v121, v74
	v_add_f32_e32 v109, v109, v171
	v_cndmask_b32_e64 v108, v196, v108, s[0:1]
	v_cmp_le_i32_e64 s[0:1], v159, v118
	v_sub_f32_e32 v173, v121, v75
	v_add_f32_e32 v110, v110, v172
	v_cndmask_b32_e64 v109, v196, v109, s[0:1]
	v_cmp_le_i32_e64 s[0:1], v161, v118
	s_waitcnt lgkmcnt(0)
;   __device__ __forceinline__ float* r() const { return (float*)(b + L::o_r); }
; template <bool FOX, int G>
; __device__ __forceinline__ void p3_attn(const Ptrs<G>& w, int seq, int h, int qb, bfu* sm, int kslot) {
;     ...
;       if (FOX) {
;         float4 Fs[4];
; #pragma unroll
;         for (int i = 0; i < 4; ++i) Fs[i] = *(const float4*)(Fh + s0 + 16 * i + 4 * g);
; #pragma unroll
;         for (int j = 0; j < 2; ++j) {
;           const int t = qrow0 + 16 * j + c15;
;           float mx = -1e30f;
; #pragma unroll
;           for (int i = 0; i < 4; ++i) {
;             const float fs[4] = {Fs[i].x, Fs[i].y, Fs[i].z, Fs[i].w};
; #pragma unroll
;             for (int r = 0; r < 4; ++r) {
;               const int s = s0 + 16 * i + 4 * g + r;
;               float z = S[i][j][r] + (Ft[j] - fs[r]);
;               z = (s <= t) ? z : -1e30f;
;               S[i][j][r] = z; mx = fmaxf(mx, z);
;             }
;           }
;           mx = fmaxf(mx, __shfl_xor(mx, 16)); mx = fmaxf(mx, __shfl_xor(mx, 32));
;           const float mnew = fmaxf(mrun[j], mx);
;           const float alpha = __expf(mrun[j] - mnew);
;           mrun[j] = mnew;
;           float ps = 0.f;
; #pragma unroll
;           for (int i = 0; i < 4; ++i)
; #pragma unroll
;             for (int r = 0; r < 4; ++r) { float p = __expf(S[i][j][r] - mnew); S[i][j][r] = p; ps += p; }
;           ps += __shfl_xor(ps, 16); ps += __shfl_xor(ps, 32);
;           lsum[j] = lsum[j] * alpha + ps;
; #pragma unroll
;           for (int dt = 0; dt < 4; ++dt) O[dt][j] = O[dt][j] * alpha;
	v_mfma_f32_16x16x32_bf16 v[148:151], v[92:95], v[16:19], v[184:187]
	v_add_f32_e32 v111, v111, v173
	v_cndmask_b32_e64 v110, v196, v110, s[0:1]
	v_cmp_le_i32_e64 s[0:1], v163, v118
	v_sub_f32_e32 v184, v121, v68
	v_add_u32_e32 v167, 0x61, v142
	v_sub_f32_e32 v185, v121, v69
	v_add_f32_e32 v104, v104, v184
	v_cndmask_b32_e64 v111, v196, v111, s[0:1]
	v_cmp_le_i32_e64 s[0:1], v165, v118
	v_sub_f32_e32 v186, v121, v70
	v_add_f32_e32 v105, v105, v185
	v_cndmask_b32_e64 v104, v196, v104, s[0:1]
	v_cmp_le_i32_e64 s[0:1], v167, v118
	v_sub_f32_e32 v187, v121, v71
	v_add_f32_e32 v106, v106, v186
	v_cndmask_b32_e64 v105, v196, v105, s[0:1]
	v_cmp_le_i32_e64 s[0:1], v169, v118
	v_add_f32_e32 v107, v107, v187
	v_add_u32_e32 v184, 0x70, v142
	v_cndmask_b32_e64 v106, v196, v106, s[0:1]
	v_cmp_le_i32_e64 s[0:1], v198, v118
	v_max3_f32 v144, v100, s2, v101
	v_add_f32_e32 v146, v148, v146
	v_cndmask_b32_e64 v107, v196, v107, s[0:1]
	v_cmp_le_i32_e64 s[0:1], v184, v118
	v_max3_f32 v144, v144, v102, v103
	v_add_u32_e32 v186, 0x71, v142
	v_cndmask_b32_e64 v185, v196, v146, s[0:1]
	v_sub_f32_e32 v146, v121, v65
	v_max3_f32 v144, v144, v108, v109
	v_add_f32_e32 v146, v149, v146
	v_cmp_le_i32_e64 s[0:1], v186, v118
	v_max3_f32 v144, v144, v110, v111
	v_add_u32_e32 v187, 0x72, v142
	v_cndmask_b32_e64 v149, v196, v146, s[0:1]
	v_sub_f32_e32 v146, v121, v66
	v_max3_f32 v144, v144, v104, v105
	v_add_f32_e32 v146, v150, v146
	v_cmp_le_i32_e64 s[0:1], v187, v118
	v_sub_f32_e32 v142, v121, v67
	v_max3_f32 v144, v144, v106, v107
	v_cndmask_b32_e64 v199, v196, v146, s[0:1]
	v_add_f32_e32 v142, v151, v142
	v_cmp_le_i32_e64 s[0:1], v200, v118
	v_max3_f32 v144, v144, v185, v149
	v_sub_f32_e32 v72, v120, v72
	v_cndmask_b32_e64 v151, v196, v142, s[0:1]
	v_max3_f32 v142, v144, v199, v151
	v_mfma_f32_16x16x32_bf16 v[88:91], v[88:91], v[20:23], 0
	v_add_f32_e32 v72, v84, v72
	v_sub_f32_e32 v73, v120, v73
	ds_bpermute_b32 v144, v119, v142
	v_cndmask_b32_e32 v72, v72, v196, vcc
	v_add_f32_e32 v73, v85, v73
	v_cmp_le_i32_e32 vcc, v159, v117
	v_sub_f32_e32 v74, v120, v74
	v_add_f32_e32 v74, v86, v74
	v_cndmask_b32_e32 v73, v196, v73, vcc
	v_cmp_le_i32_e32 vcc, v161, v117
	v_sub_f32_e32 v75, v120, v75
	v_add_f32_e32 v75, v87, v75
	v_cndmask_b32_e32 v74, v196, v74, vcc
	v_cmp_le_i32_e32 vcc, v163, v117
	v_sub_f32_e32 v68, v120, v68
	v_mfma_f32_16x16x32_bf16 v[170:173], v[92:95], v[24:27], v[88:91]
	v_cmp_le_i32_e64 s[0:1], v143, v117
	v_cndmask_b32_e32 v75, v196, v75, vcc
	v_add_f32_e32 v68, v96, v68
	v_cmp_le_i32_e32 vcc, v165, v117
	v_sub_f32_e32 v69, v120, v69
	v_cndmask_b32_e64 v76, v196, v76, s[0:1]
	v_cmp_lt_i32_e64 s[0:1], v143, v117
	v_sub_f32_e32 v78, v120, v78
	v_cndmask_b32_e32 v68, v196, v68, vcc
	v_add_f32_e32 v69, v97, v69
	v_cmp_le_i32_e32 vcc, v167, v117
	v_sub_f32_e32 v70, v120, v70
	s_waitcnt lgkmcnt(0)
	v_max_f32_e32 v144, v144, v144
	v_cndmask_b32_e64 v77, v196, v77, s[0:1]
	v_add_f32_e32 v78, v82, v78
	v_cmp_le_i32_e64 s[0:1], v145, v117
	v_sub_f32_e32 v79, v120, v79
	v_cndmask_b32_e32 v69, v196, v69, vcc
	v_add_f32_e32 v70, v98, v70
	v_cmp_le_i32_e32 vcc, v169, v117
	v_sub_f32_e32 v71, v120, v71
	v_max_f32_e32 v142, v142, v144
	v_cndmask_b32_e64 v78, v196, v78, s[0:1]
	v_add_f32_e32 v79, v83, v79
	v_cmp_le_i32_e64 s[0:1], v147, v117
	v_cndmask_b32_e32 v70, v196, v70, vcc
	v_add_f32_e32 v71, v99, v71
	v_cmp_le_i32_e32 vcc, v198, v117
	ds_bpermute_b32 v144, v133, v142
	v_max3_f32 v80, v76, s2, v77
	v_cndmask_b32_e64 v79, v196, v79, s[0:1]
	v_cndmask_b32_e32 v71, v196, v71, vcc
	v_add_f32_e32 v64, v170, v64
	v_cmp_le_i32_e32 vcc, v184, v117
	v_max3_f32 v80, v80, v78, v79
	v_max3_f32 v80, v80, v72, v73
	v_cndmask_b32_e32 v81, v196, v64, vcc
	v_sub_f32_e32 v64, v120, v65
	v_add_f32_e32 v64, v171, v64
	v_cmp_le_i32_e32 vcc, v186, v117
	v_sub_f32_e32 v65, v120, v66
	v_max3_f32 v80, v80, v74, v75
	v_cndmask_b32_e32 v82, v196, v64, vcc
	v_add_f32_e32 v65, v172, v65
	v_cmp_le_i32_e32 vcc, v187, v117
	v_max3_f32 v80, v80, v68, v69
	s_waitcnt lgkmcnt(0)
	v_max3_f32 v157, v141, v142, v144
	v_cndmask_b32_e32 v84, v196, v65, vcc
	v_sub_f32_e32 v65, v120, v67
	v_max3_f32 v80, v80, v70, v71
	v_add_f32_e32 v65, v173, v65
	v_cmp_le_i32_e32 vcc, v200, v117
	v_sub_f32_e32 v89, v100, v157
	v_max3_f32 v64, v80, v81, v82
	v_cndmask_b32_e32 v85, v196, v65, vcc
	v_mul_f32_e32 v89, 0x3fb8aa3b, v89
	v_max3_f32 v64, v64, v84, v85
	v_exp_f32_e32 v164, v89
	v_sub_f32_e32 v89, v101, v157
	ds_bpermute_b32 v65, v119, v64
	v_mul_f32_e32 v89, 0x3fb8aa3b, v89
	v_exp_f32_e32 v166, v89
	v_sub_f32_e32 v89, v102, v157
	v_mul_f32_e32 v89, 0x3fb8aa3b, v89
	v_exp_f32_e32 v142, v89
	v_sub_f32_e32 v89, v103, v157
	v_mul_f32_e32 v89, 0x3fb8aa3b, v89
	s_waitcnt lgkmcnt(0)
	v_max_f32_e32 v65, v65, v65
	v_exp_f32_e32 v144, v89
	v_sub_f32_e32 v89, v108, v157
	v_max_f32_e32 v64, v64, v65
	v_mul_f32_e32 v89, 0x3fb8aa3b, v89
	ds_bpermute_b32 v65, v133, v64
	v_exp_f32_e32 v146, v89
	v_sub_f32_e32 v89, v109, v157
	v_mul_f32_e32 v89, 0x3fb8aa3b, v89
	v_exp_f32_e32 v148, v89
	v_sub_f32_e32 v89, v110, v157
	v_mul_f32_e32 v89, 0x3fb8aa3b, v89
	v_exp_f32_e32 v150, v89
	v_sub_f32_e32 v89, v111, v157
	s_waitcnt lgkmcnt(0)
; template <bool FOX, int G>
; __device__ __forceinline__ void p3_attn(const Ptrs<G>& w, int seq, int h, int qb, bfu* sm, int kslot) {
;     ...
;           const float mnew = fmaxf(mrun[j], mx);
;           const float alpha = __expf(mrun[j] - mnew);
;           mrun[j] = mnew;
;           float ps = 0.f;
; #pragma unroll
;           for (int i = 0; i < 4; ++i)
; #pragma unroll
;             for (int r = 0; r < 4; ++r) { float p = __expf(S[i][j][r] - mnew); S[i][j][r] = p; ps += p; }
;           ps += __shfl_xor(ps, 16); ps += __shfl_xor(ps, 32);
;           lsum[j] = lsum[j] * alpha + ps;
; #pragma unroll
;           for (int dt = 0; dt < 4; ++dt) O[dt][j] = O[dt][j] * alpha;
;         }
;       } else {
; #pragma unroll
;         for (int j = 0; j < 2; ++j) {
;           const int t = qrow0 + 16 * j + c15;
;           float LR[4][4];
; #pragma unroll
;           for (int i = 0; i < 4; ++i)
; #pragma unroll
;             for (int r = 0; r < 4; ++r) {
;               const int s = s0 + 16 * i + 4 * g + r;
;               const float z = S[i][j][r];
;               const float lp = __logf(1.f + __expf(-fabsf(z)));
;               const bool valid = s < t;
;               S[i][j][r] = fminf(z, 0.f) - lp;
;               LR[i][r] = valid ? (fminf(-z, 0.f) - lp) : 0.f;
;             }
;           float running = Rrun[j];
; #pragma unroll
;           for (int i = 3; i >= 0; --i) {
;             const float c = (LR[i][0] + LR[i][1]) + (LR[i][2] + LR[i][3]);
;             const float v0 = __shfl(c, c15), v1 = __shfl(c, c15 + 16), v2 = __shfl(c, c15 + 32), v3 = __shfl(c, c15 + 48);
;             const float Eg = (g < 1 ? v1 : 0.f) + (g < 2 ? v2 : 0.f) + (g < 3 ? v3 : 0.f);
;             const float b3 = running + Eg, b2 = b3 + LR[i][3], b1 = b2 + LR[i][2], b0 = b1 + LR[i][1];
;             const int sb = s0 + 16 * i + 4 * g;
;             S[i][j][0] = (sb + 0 < t) ? __expf(S[i][j][0] + b0) : 0.f;
;             S[i][j][1] = (sb + 1 < t) ? __expf(S[i][j][1] + b1) : 0.f;
;             S[i][j][2] = (sb + 2 < t) ? __expf(S[i][j][2] + b2) : 0.f;
;             S[i][j][3] = (sb + 3 < t) ? __expf(S[i][j][3] + b3) : 0.f;
;             running += (v0 + v1) + (v2 + v3);
;           }
;           Rrun[j] = running;
;         }
;       }
; #pragma unroll
;       for (int sb = 0; sb < 2; ++sb) {
;         bf16x8 Pb[2];
; #pragma unroll
;         for (int j = 0; j < 2; ++j) {
	v_max3_f32 v67, v140, v64, v65
	v_mul_f32_e32 v89, 0x3fb8aa3b, v89
	v_sub_f32_e32 v64, v140, v67
	v_exp_f32_e32 v108, v89
	v_sub_f32_e32 v89, v104, v157
	v_mul_f32_e32 v66, 0x3fb8aa3b, v64
	v_sub_f32_e32 v64, v76, v67
	v_mul_f32_e32 v89, 0x3fb8aa3b, v89
	v_mul_f32_e32 v64, 0x3fb8aa3b, v64
	v_exp_f32_e32 v110, v89
	v_sub_f32_e32 v89, v105, v157
	v_exp_f32_e32 v165, v64
	v_sub_f32_e32 v64, v77, v67
	v_mul_f32_e32 v89, 0x3fb8aa3b, v89
	v_mul_f32_e32 v64, 0x3fb8aa3b, v64
	v_exp_f32_e32 v92, v89
	v_sub_f32_e32 v89, v106, v157
	v_exp_f32_e32 v167, v64
	v_sub_f32_e32 v64, v78, v67
	v_mul_f32_e32 v89, 0x3fb8aa3b, v89
	v_mul_f32_e32 v64, 0x3fb8aa3b, v64
	v_exp_f32_e32 v94, v89
	v_sub_f32_e32 v89, v107, v157
	v_exp_f32_e32 v143, v64
	v_sub_f32_e32 v64, v79, v67
	v_mul_f32_e32 v89, 0x3fb8aa3b, v89
	v_mul_f32_e32 v64, 0x3fb8aa3b, v64
	v_exp_f32_e32 v100, v89
	v_sub_f32_e32 v89, v185, v157
	v_exp_f32_e32 v145, v64
	v_sub_f32_e32 v64, v72, v67
	v_mul_f32_e32 v89, 0x3fb8aa3b, v89
	v_mul_f32_e32 v64, 0x3fb8aa3b, v64
	v_exp_f32_e32 v102, v89
	v_sub_f32_e32 v89, v149, v157
	v_exp_f32_e32 v147, v64
	v_sub_f32_e32 v64, v73, v67
	v_mul_f32_e32 v89, 0x3fb8aa3b, v89
	v_mul_f32_e32 v64, 0x3fb8aa3b, v64
	v_exp_f32_e32 v104, v89
	v_sub_f32_e32 v89, v199, v157
	v_exp_f32_e32 v149, v64
	v_sub_f32_e32 v64, v74, v67
	v_mul_f32_e32 v89, 0x3fb8aa3b, v89
	v_mul_f32_e32 v64, 0x3fb8aa3b, v64
	v_exp_f32_e32 v106, v89
	v_sub_f32_e32 v89, v151, v157
	v_exp_f32_e32 v151, v64
	v_sub_f32_e32 v64, v75, v67
	v_mul_f32_e32 v64, 0x3fb8aa3b, v64
	v_exp_f32_e32 v109, v64
	v_sub_f32_e32 v64, v68, v67
	v_sub_f32_e32 v68, v69, v67
	v_mul_f32_e32 v68, 0x3fb8aa3b, v68
	v_exp_f32_e32 v93, v68
	v_sub_f32_e32 v68, v70, v67
	v_mul_f32_e32 v68, 0x3fb8aa3b, v68
	v_exp_f32_e32 v95, v68
	v_sub_f32_e32 v68, v71, v67
	v_sub_f32_e32 v88, v141, v157
	v_mul_f32_e32 v68, 0x3fb8aa3b, v68
	v_mul_f32_e32 v88, 0x3fb8aa3b, v88
	v_exp_f32_e32 v101, v68
	v_sub_f32_e32 v68, v81, v67
	v_exp_f32_e32 v88, v88
	v_mul_f32_e32 v68, 0x3fb8aa3b, v68
	v_add_u32_e32 v87, 0x2000, v168
	v_exp_f32_e32 v103, v68
	ds_read2_b64 v[68:71], v87 offset0:128 offset1:132
	v_mul_f32_e32 v89, 0x3fb8aa3b, v89
	v_exp_f32_e32 v90, v89
	v_pk_mul_f32 v[62:63], v[62:63], v[88:89] op_sel_hi:[1,0]
	v_pk_mul_f32 v[60:61], v[60:61], v[88:89] op_sel_hi:[1,0]
	v_pk_mul_f32 v[58:59], v[58:59], v[88:89] op_sel_hi:[1,0]
	v_pk_mul_f32 v[56:57], v[56:57], v[88:89] op_sel_hi:[1,0]
	v_pk_mul_f32 v[54:55], v[54:55], v[88:89] op_sel_hi:[1,0]
	v_pk_mul_f32 v[52:53], v[52:53], v[88:89] op_sel_hi:[1,0]
	v_pk_mul_f32 v[50:51], v[50:51], v[88:89] op_sel_hi:[1,0]
	v_pk_mul_f32 v[48:49], v[48:49], v[88:89] op_sel_hi:[1,0]
	v_exp_f32_e32 v89, v66
	v_add_u32_e32 v96, 0x2800, v168
	v_sub_f32_e32 v66, v82, v67
	ds_read2_b64 v[80:83], v96 offset0:160 offset1:164
	v_mul_f32_e32 v86, 0x3fb8aa3b, v66
	v_mov_b32_e32 v66, v89
	v_pk_mul_f32 v[30:31], v[30:31], v[66:67] op_sel_hi:[1,0]
	v_pk_mul_f32 v[28:29], v[28:29], v[66:67] op_sel_hi:[1,0]
	v_cvt_pk_bf16_f32 v72, v164, v166
	v_cvt_pk_bf16_f32 v73, v142, v144
	v_cvt_pk_bf16_f32 v74, v146, v148
	v_cvt_pk_bf16_f32 v75, v150, v108
	v_cvt_pk_bf16_f32 v76, v165, v167
	v_cvt_pk_bf16_f32 v77, v143, v145
	v_cvt_pk_bf16_f32 v78, v147, v149
	v_cvt_pk_bf16_f32 v79, v151, v109
	v_exp_f32_e32 v105, v86
	v_add_u32_e32 v86, 0x3000, v168
	s_waitcnt lgkmcnt(1)
	v_mfma_f32_16x16x32_bf16 v[60:63], v[68:71], v[72:75], v[60:63]
	v_mul_f32_e64 v10, v10, v66
	v_mul_f32_e64 v11, v11, v66
	v_pk_mul_f32 v[8:9], v[8:9], v[66:67] op_sel_hi:[1,0]
	v_add_u32_e32 v97, 0x3800, v168
	v_mfma_f32_16x16x32_bf16 v[28:31], v[68:71], v[76:79], v[28:31]
	ds_read2_b64 v[68:71], v86 offset0:192 offset1:196
	v_mul_f32_e32 v64, 0x3fb8aa3b, v64
	v_exp_f32_e32 v111, v64
	s_waitcnt lgkmcnt(1)
	v_mfma_f32_16x16x32_bf16 v[56:59], v[80:83], v[72:75], v[56:59]
	v_add_f32_e64 v64, v164, 0
	v_add_f32_e64 v65, v165, 0
	v_pk_mul_f32 v[6:7], v[6:7], v[66:67] op_sel_hi:[1,0]
	v_pk_add_f32 v[64:65], v[166:167], v[64:65]
	v_mfma_f32_16x16x32_bf16 v[8:11], v[80:83], v[76:79], v[8:11]
	ds_read2_b64 v[80:83], v97 offset0:224 offset1:228
	v_pk_mul_f32 v[4:5], v[4:5], v[66:67] op_sel_hi:[1,0]
	v_pk_add_f32 v[64:65], v[142:143], v[64:65]
	s_waitcnt lgkmcnt(1)
	v_mfma_f32_16x16x32_bf16 v[52:55], v[68:71], v[72:75], v[52:55]
	v_add_f32_e64 v64, v144, v64
	v_add_f32_e64 v65, v145, v65
	v_sub_f32_e32 v84, v84, v67
	v_pk_add_f32 v[64:65], v[146:147], v[64:65]
	v_mfma_f32_16x16x32_bf16 v[4:7], v[68:71], v[76:79], v[4:7]
	v_sub_f32_e32 v68, v85, v67
	v_mul_f32_e32 v68, 0x3fb8aa3b, v68
	v_exp_f32_e32 v91, v68
	ds_read2_b64 v[68:71], v87 offset0:136 offset1:140
	v_pk_add_f32 v[64:65], v[148:149], v[64:65]
	v_pk_mul_f32 v[2:3], v[2:3], v[66:67] op_sel_hi:[1,0]
	v_pk_add_f32 v[64:65], v[150:151], v[64:65]
	v_pk_mul_f32 v[0:1], v[0:1], v[66:67] op_sel_hi:[1,0]
	v_mul_f32_e32 v84, 0x3fb8aa3b, v84
	s_waitcnt lgkmcnt(1)
	v_mfma_f32_16x16x32_bf16 v[48:51], v[80:83], v[72:75], v[48:51]
	v_add_f32_e64 v64, v108, v64
	v_add_f32_e64 v65, v109, v65
	v_exp_f32_e32 v107, v84
	v_pk_add_f32 v[64:65], v[110:111], v[64:65]
	v_mfma_f32_16x16x32_bf16 v[0:3], v[80:83], v[76:79], v[0:3]
	ds_read2_b64 v[80:83], v96 offset0:168 offset1:172
	v_pk_add_f32 v[64:65], v[92:93], v[64:65]
	v_cvt_pk_bf16_f32 v72, v110, v92
	v_pk_add_f32 v[64:65], v[94:95], v[64:65]
	v_cvt_pk_bf16_f32 v73, v94, v100
	v_pk_add_f32 v[64:65], v[100:101], v[64:65]
	v_cvt_pk_bf16_f32 v74, v102, v104
	v_cvt_pk_bf16_f32 v75, v106, v90
	v_cvt_pk_bf16_f32 v76, v111, v93
	v_cvt_pk_bf16_f32 v77, v95, v101
	v_cvt_pk_bf16_f32 v78, v103, v105
	v_cvt_pk_bf16_f32 v79, v107, v91
	v_pk_add_f32 v[64:65], v[102:103], v[64:65]
	s_waitcnt lgkmcnt(1)
	v_mfma_f32_16x16x32_bf16 v[60:63], v[68:71], v[72:75], v[60:63]
	v_add_f32_e64 v64, v104, v64
	v_add_f32_e64 v65, v105, v65
	v_mov_b32_e32 v140, v67
	v_pk_add_f32 v[64:65], v[106:107], v[64:65]
	v_mfma_f32_16x16x32_bf16 v[28:31], v[68:71], v[76:79], v[28:31]
	ds_read2_b64 v[68:71], v86 offset0:200 offset1:204
	v_pk_add_f32 v[64:65], v[90:91], v[64:65]
	ds_bpermute_b32 v84, v119, v64
	s_waitcnt lgkmcnt(2)
	v_mfma_f32_16x16x32_bf16 v[56:59], v[80:83], v[72:75], v[56:59]
	ds_bpermute_b32 v85, v119, v65
	v_mov_b32_e32 v141, v157
	s_waitcnt lgkmcnt(0)
	v_pk_add_f32 v[64:65], v[64:65], v[84:85]
	v_mfma_f32_16x16x32_bf16 v[8:11], v[80:83], v[76:79], v[8:11]
	ds_read2_b64 v[80:83], v97 offset0:232 offset1:236
	v_mfma_f32_16x16x32_bf16 v[52:55], v[68:71], v[72:75], v[52:55]
	v_mfma_f32_16x16x32_bf16 v[4:7], v[68:71], v[76:79], v[4:7]
	ds_bpermute_b32 v68, v133, v64
	ds_bpermute_b32 v69, v133, v65
	s_waitcnt lgkmcnt(0)
	v_pk_add_f32 v[64:65], v[64:65], v[68:69]
	v_mfma_f32_16x16x32_bf16 v[48:51], v[80:83], v[72:75], v[48:51]
	v_fma_f32 v128, v128, v88, v64
	v_fma_f32 v129, v129, v89, v65
	v_mfma_f32_16x16x32_bf16 v[0:3], v[80:83], v[76:79], v[0:3]
	s_branch .LBB0_319

; __device__ __forceinline__ float bf2f(bfu h) { return __uint_as_float(((unsigned)h) << 16); }
; __device__ __forceinline__ float sigm(float x) { return 1.f / (1.f + __expf(-x)); }
;   __device__ __forceinline__ bfu* glu() const { return (bfu*)(b + L::o_glu); }
; template <int G>
; __device__ __forceinline__ void p2_conformer(const Params& P, const Ptrs<G>& w, int layer, int item, float* cv, int kslot) {
;     ...
;     for (int sr = 0; sr < 62; ++sr) {
;       const int s = t0 - 30 + sr;
;       float h0 = 0.f;
;       if (s >= 0) {
;         const bfu* gp = w.glu() + (seqbase + s) * 1024 + c;
;         h0 = bf2f(gp[0]) * sigm(bf2f(gp[512]));
;       }
; #pragma unroll
;       for (int tr = 0; tr < 32; ++tr) {
;         const int j = sr - tr;
;         if (j >= 0 && j <= 30) a[tr] += wj[j] * h0;
;       }
;     }
.LBB0_348:
	v_lshl_add_u64 v[4:5], v[4:5], 0, s[2:3]
	s_mov_b64 s[100:101], 0x1000
	v_lshl_add_u64 v[100:101], v[4:5], 0, s[100:101]
	s_mov_b64 s[100:101], 0x2000
	global_load_ushort v102, v[100:101], off offset:-4096
	global_load_ushort v102, v[100:101], off offset:-3072
	global_load_ushort v102, v[100:101], off offset:-2048
	global_load_ushort v102, v[100:101], off offset:-1024
	global_load_ushort v102, v[100:101], off
	global_load_ushort v102, v[100:101], off offset:1024
	global_load_ushort v102, v[100:101], off offset:2048
	global_load_ushort v102, v[100:101], off offset:3072
	v_lshl_add_u64 v[100:101], v[100:101], 0, s[100:101]
	global_load_ushort v102, v[100:101], off offset:-4096
	global_load_ushort v102, v[100:101], off offset:-3072
	global_load_ushort v102, v[100:101], off offset:-2048
	global_load_ushort v102, v[100:101], off offset:-1024
	global_load_ushort v102, v[100:101], off
	global_load_ushort v102, v[100:101], off offset:1024
	global_load_ushort v102, v[100:101], off offset:2048
	global_load_ushort v102, v[100:101], off offset:3072
	v_lshl_add_u64 v[100:101], v[100:101], 0, s[100:101]
	global_load_ushort v102, v[100:101], off offset:-4096
	global_load_ushort v102, v[100:101], off offset:-3072
	global_load_ushort v102, v[100:101], off offset:-2048
	global_load_ushort v102, v[100:101], off offset:-1024
	global_load_ushort v102, v[100:101], off
	global_load_ushort v102, v[100:101], off offset:1024
	global_load_ushort v102, v[100:101], off offset:2048
	global_load_ushort v102, v[100:101], off offset:3072
	v_lshl_add_u64 v[100:101], v[100:101], 0, s[100:101]
	global_load_ushort v102, v[100:101], off offset:-4096
	global_load_ushort v102, v[100:101], off offset:-3072
	global_load_ushort v102, v[100:101], off offset:-2048
	global_load_ushort v102, v[100:101], off offset:-1024
	global_load_ushort v102, v[100:101], off
	global_load_ushort v102, v[100:101], off offset:1024
	global_load_ushort v102, v[100:101], off offset:2048
	global_load_ushort v102, v[100:101], off offset:3072
	v_lshl_add_u64 v[100:101], v[100:101], 0, s[100:101]
	global_load_ushort v102, v[100:101], off offset:-4096
	global_load_ushort v102, v[100:101], off offset:-3072
	global_load_ushort v102, v[100:101], off offset:-2048
	global_load_ushort v102, v[100:101], off offset:-1024
	global_load_ushort v102, v[100:101], off
	global_load_ushort v102, v[100:101], off offset:1024
	global_load_ushort v102, v[100:101], off offset:2048
	global_load_ushort v102, v[100:101], off offset:3072
	v_lshl_add_u64 v[100:101], v[100:101], 0, s[100:101]
	global_load_ushort v102, v[100:101], off offset:-4096
	global_load_ushort v102, v[100:101], off offset:-3072
	global_load_ushort v102, v[100:101], off offset:-2048
	global_load_ushort v102, v[100:101], off offset:-1024
	global_load_ushort v102, v[100:101], off
	global_load_ushort v102, v[100:101], off offset:1024
	global_load_ushort v102, v[100:101], off offset:2048
	global_load_ushort v102, v[100:101], off offset:3072
	v_lshl_add_u64 v[100:101], v[100:101], 0, s[100:101]
	global_load_ushort v102, v[100:101], off offset:-4096
	global_load_ushort v102, v[100:101], off offset:-3072
	global_load_ushort v102, v[100:101], off offset:-2048
	global_load_ushort v102, v[100:101], off offset:-1024
	global_load_ushort v102, v[100:101], off
	global_load_ushort v102, v[100:101], off offset:1024
	global_load_ushort v102, v[100:101], off offset:2048
	global_load_ushort v102, v[100:101], off offset:3072
	v_lshl_add_u64 v[100:101], v[100:101], 0, s[100:101]
	global_load_ushort v102, v[100:101], off offset:-4096
	global_load_ushort v102, v[100:101], off offset:-3072
	global_load_ushort v102, v[100:101], off offset:-2048
	global_load_ushort v102, v[100:101], off offset:-1024
	global_load_ushort v102, v[100:101], off
	global_load_ushort v102, v[100:101], off offset:1024
	global_load_ushort v102, v[100:101], off offset:2048
	global_load_ushort v102, v[100:101], off offset:3072
	global_load_ushort v38, v[4:5], off offset:1024
	s_waitcnt vmcnt(1)
	v_fma_f32 v3, v68, v3, v7
	v_fmac_f32_e32 v3, v67, v8
	v_fma_f32 v8, v68, v8, v7
	v_fmac_f32_e32 v3, v66, v9
	v_fmac_f32_e32 v8, v67, v9
	v_fma_f32 v9, v68, v9, v7
	v_fmac_f32_e32 v3, v65, v10
	v_fmac_f32_e32 v8, v66, v10
	v_fmac_f32_e32 v9, v67, v10
	v_fma_f32 v10, v68, v10, v7
	v_fmac_f32_e32 v3, v64, v11
	v_fmac_f32_e32 v8, v65, v11
	v_fmac_f32_e32 v9, v66, v11
	v_fmac_f32_e32 v10, v67, v11
	v_fma_f32 v11, v68, v11, v7
	v_fmac_f32_e32 v3, v63, v12
	v_fmac_f32_e32 v8, v64, v12
	v_fmac_f32_e32 v9, v65, v12
	v_fmac_f32_e32 v10, v66, v12
	v_fmac_f32_e32 v11, v67, v12
	v_fma_f32 v12, v68, v12, v7
	v_fmac_f32_e32 v3, v62, v13
	v_fmac_f32_e32 v8, v63, v13
	v_fmac_f32_e32 v9, v64, v13
	v_fmac_f32_e32 v10, v65, v13
	v_fmac_f32_e32 v11, v66, v13
	v_fmac_f32_e32 v12, v67, v13
	v_fma_f32 v13, v68, v13, v7
	v_fmac_f32_e32 v3, v61, v14
	v_fmac_f32_e32 v8, v62, v14
	v_fmac_f32_e32 v9, v63, v14
	v_fmac_f32_e32 v10, v64, v14
	v_fmac_f32_e32 v11, v65, v14
	v_fmac_f32_e32 v12, v66, v14
	v_fmac_f32_e32 v13, v67, v14
	v_fma_f32 v14, v68, v14, v7
	v_fmac_f32_e32 v3, v60, v15
	v_fmac_f32_e32 v8, v61, v15
	v_fmac_f32_e32 v9, v62, v15
	v_fmac_f32_e32 v10, v63, v15
	v_fmac_f32_e32 v11, v64, v15
	v_fmac_f32_e32 v12, v65, v15
	v_fmac_f32_e32 v13, v66, v15
	v_fmac_f32_e32 v14, v67, v15
	v_fma_f32 v15, v68, v15, v7
	v_fmac_f32_e32 v3, v59, v17
	v_fmac_f32_e32 v8, v60, v17
	v_fmac_f32_e32 v9, v61, v17
	v_fmac_f32_e32 v10, v62, v17
	v_fmac_f32_e32 v11, v63, v17
	v_fmac_f32_e32 v12, v64, v17
	v_fmac_f32_e32 v13, v65, v17
	v_fmac_f32_e32 v14, v66, v17
	v_fmac_f32_e32 v15, v67, v17
	v_fma_f32 v17, v68, v17, v7
	v_fmac_f32_e32 v3, v58, v18
	v_fmac_f32_e32 v8, v59, v18
	v_fmac_f32_e32 v9, v60, v18
	v_fmac_f32_e32 v10, v61, v18
	v_fmac_f32_e32 v11, v62, v18
	v_fmac_f32_e32 v12, v63, v18
	v_fmac_f32_e32 v13, v64, v18
	v_fmac_f32_e32 v14, v65, v18
	v_fmac_f32_e32 v15, v66, v18
	v_fmac_f32_e32 v17, v67, v18
	v_fma_f32 v18, v68, v18, v7
	v_fmac_f32_e32 v3, v57, v19
	v_fmac_f32_e32 v8, v58, v19
	v_fmac_f32_e32 v9, v59, v19
	v_fmac_f32_e32 v10, v60, v19
	v_fmac_f32_e32 v11, v61, v19
	v_fmac_f32_e32 v12, v62, v19
	v_fmac_f32_e32 v13, v63, v19
	v_fmac_f32_e32 v14, v64, v19
	v_fmac_f32_e32 v15, v65, v19
	v_fmac_f32_e32 v17, v66, v19
	v_fmac_f32_e32 v18, v67, v19
	v_fma_f32 v19, v68, v19, v7
	v_fmac_f32_e32 v3, v56, v20
	s_waitcnt vmcnt(0)
; __device__ __forceinline__ float bf2f(bfu h) { return __uint_as_float(((unsigned)h) << 16); }
; __device__ __forceinline__ float sigm(float x) { return 1.f / (1.f + __expf(-x)); }
;   __device__ __forceinline__ bfu* glu() const { return (bfu*)(b + L::o_glu); }
; template <int G>
; __device__ __forceinline__ void p2_conformer(const Params& P, const Ptrs<G>& w, int layer, int item, float* cv, int kslot) {
;     ...
;     for (int sr = 0; sr < 62; ++sr) {
;       const int s = t0 - 30 + sr;
;       float h0 = 0.f;
;       if (s >= 0) {
;         const bfu* gp = w.glu() + (seqbase + s) * 1024 + c;
;         h0 = bf2f(gp[0]) * sigm(bf2f(gp[512]));
;       }
; #pragma unroll
;       for (int tr = 0; tr < 32; ++tr) {
;         const int j = sr - tr;
;         if (j >= 0 && j <= 30) a[tr] += wj[j] * h0;
;       }
;     }
	v_lshlrev_b32_e32 v38, 16, v38
	v_mul_f32_e32 v38, 0xbfb8aa3b, v38
	v_exp_f32_e32 v38, v38
	v_fmac_f32_e32 v8, v57, v20
	v_fmac_f32_e32 v9, v58, v20
	v_fmac_f32_e32 v10, v59, v20
	v_add_f32_e32 v38, 1.0, v38
	v_div_scale_f32 v69, s[72:73], v38, v38, 1.0
	v_rcp_f32_e32 v70, v69
	v_fmac_f32_e32 v11, v60, v20
	v_fmac_f32_e32 v12, v61, v20
	v_fmac_f32_e32 v13, v62, v20
	v_fma_f32 v71, -v69, v70, 1.0
	v_fmac_f32_e32 v70, v71, v70
	v_div_scale_f32 v71, vcc, 1.0, v38, 1.0
	v_mul_f32_e32 v72, v71, v70
	v_fma_f32 v73, -v69, v72, v71
	v_fmac_f32_e32 v72, v73, v70
	v_fma_f32 v69, -v69, v72, v71
	v_div_fmas_f32 v69, v69, v70, v72
	v_div_fixup_f32 v38, v69, v38, 1.0
	global_load_ushort v69, v[4:5], off
	v_fmac_f32_e32 v14, v63, v20
	v_fmac_f32_e32 v15, v64, v20
	v_fmac_f32_e32 v17, v65, v20
	v_fmac_f32_e32 v18, v66, v20
	v_fmac_f32_e32 v19, v67, v20
	v_fma_f32 v20, v68, v20, v7
	v_fmac_f32_e32 v3, v55, v21
	v_fmac_f32_e32 v8, v56, v21
	v_fmac_f32_e32 v9, v57, v21
	v_fmac_f32_e32 v10, v58, v21
	v_fmac_f32_e32 v11, v59, v21
	v_fmac_f32_e32 v12, v60, v21
	v_fmac_f32_e32 v13, v61, v21
	v_fmac_f32_e32 v14, v62, v21
	v_fmac_f32_e32 v15, v63, v21
	v_fmac_f32_e32 v17, v64, v21
	v_fmac_f32_e32 v18, v65, v21
	v_fmac_f32_e32 v19, v66, v21
	v_fmac_f32_e32 v20, v67, v21
	v_fma_f32 v21, v68, v21, v7
	v_fmac_f32_e32 v3, v54, v22
	v_fmac_f32_e32 v8, v55, v22
	v_fmac_f32_e32 v9, v56, v22
	v_fmac_f32_e32 v10, v57, v22
	v_fmac_f32_e32 v11, v58, v22
	v_fmac_f32_e32 v12, v59, v22
	v_fmac_f32_e32 v13, v60, v22
	v_fmac_f32_e32 v14, v61, v22
	v_fmac_f32_e32 v15, v62, v22
	v_fmac_f32_e32 v17, v63, v22
	v_fmac_f32_e32 v18, v64, v22
	v_fmac_f32_e32 v19, v65, v22
	v_fmac_f32_e32 v20, v66, v22
	v_fmac_f32_e32 v21, v67, v22
	v_fma_f32 v22, v68, v22, v7
	v_fmac_f32_e32 v3, v53, v23
	v_fmac_f32_e32 v8, v54, v23
	v_fmac_f32_e32 v9, v55, v23
	v_fmac_f32_e32 v10, v56, v23
	v_fmac_f32_e32 v11, v57, v23
	v_fmac_f32_e32 v12, v58, v23
	v_fmac_f32_e32 v13, v59, v23
	v_fmac_f32_e32 v14, v60, v23
	v_fmac_f32_e32 v15, v61, v23
	v_fmac_f32_e32 v17, v62, v23
	v_fmac_f32_e32 v18, v63, v23
	v_fmac_f32_e32 v19, v64, v23
	v_fmac_f32_e32 v20, v65, v23
	v_fmac_f32_e32 v21, v66, v23
	v_fmac_f32_e32 v22, v67, v23
	v_fma_f32 v23, v68, v23, v7
	v_fmac_f32_e32 v3, v52, v24
	v_fmac_f32_e32 v8, v53, v24
	v_fmac_f32_e32 v9, v54, v24
	v_fmac_f32_e32 v10, v55, v24
	v_fmac_f32_e32 v11, v56, v24
	v_fmac_f32_e32 v12, v57, v24
	v_fmac_f32_e32 v13, v58, v24
	v_fmac_f32_e32 v14, v59, v24
	v_fmac_f32_e32 v15, v60, v24
	v_fmac_f32_e32 v17, v61, v24
	v_fmac_f32_e32 v18, v62, v24
	v_fmac_f32_e32 v19, v63, v24
	v_fmac_f32_e32 v20, v64, v24
	v_fmac_f32_e32 v21, v65, v24
	v_fmac_f32_e32 v22, v66, v24
	v_fmac_f32_e32 v23, v67, v24
	v_fma_f32 v24, v68, v24, v7
	v_fmac_f32_e32 v3, v51, v25
	v_fmac_f32_e32 v8, v52, v25
	v_fmac_f32_e32 v9, v53, v25
	v_fmac_f32_e32 v10, v54, v25
	v_fmac_f32_e32 v11, v55, v25
	v_fmac_f32_e32 v12, v56, v25
	v_fmac_f32_e32 v13, v57, v25
	v_fmac_f32_e32 v14, v58, v25
	v_fmac_f32_e32 v15, v59, v25
	v_fmac_f32_e32 v17, v60, v25
	v_fmac_f32_e32 v18, v61, v25
	s_waitcnt vmcnt(0)
	v_lshlrev_b32_e32 v69, 16, v69
	v_mul_f32_e32 v38, v38, v69
	global_load_ushort v69, v[4:5], off offset:3072
	v_fmac_f32_e32 v19, v62, v25
	v_fmac_f32_e32 v20, v63, v25
	v_fmac_f32_e32 v21, v64, v25
	v_fmac_f32_e32 v22, v65, v25
	v_fmac_f32_e32 v23, v66, v25
	v_fmac_f32_e32 v24, v67, v25
	v_fma_f32 v25, v68, v25, v7
	v_fmac_f32_e32 v3, v50, v26
	v_fmac_f32_e32 v8, v51, v26
	v_fmac_f32_e32 v9, v52, v26
	v_fmac_f32_e32 v10, v53, v26
	v_fmac_f32_e32 v11, v54, v26
	v_fmac_f32_e32 v12, v55, v26
	v_fmac_f32_e32 v13, v56, v26
	v_fmac_f32_e32 v14, v57, v26
	v_fmac_f32_e32 v15, v58, v26
	v_fmac_f32_e32 v17, v59, v26
	v_fmac_f32_e32 v18, v60, v26
	v_fmac_f32_e32 v19, v61, v26
	v_fmac_f32_e32 v20, v62, v26
	v_fmac_f32_e32 v21, v63, v26
	v_fmac_f32_e32 v22, v64, v26
	v_fmac_f32_e32 v23, v65, v26
	v_fmac_f32_e32 v24, v66, v26
	v_fmac_f32_e32 v25, v67, v26
	v_fma_f32 v26, v68, v26, v7
	v_fmac_f32_e32 v3, v49, v27
	v_fmac_f32_e32 v8, v50, v27
	v_fmac_f32_e32 v9, v51, v27
	v_fmac_f32_e32 v10, v52, v27
	v_fmac_f32_e32 v11, v53, v27
	v_fmac_f32_e32 v12, v54, v27
	v_fmac_f32_e32 v13, v55, v27
	v_fmac_f32_e32 v14, v56, v27
	v_fmac_f32_e32 v15, v57, v27
	v_fmac_f32_e32 v17, v58, v27
	v_fmac_f32_e32 v18, v59, v27
	v_fmac_f32_e32 v19, v60, v27
	v_fmac_f32_e32 v20, v61, v27
	v_fmac_f32_e32 v21, v62, v27
	v_fmac_f32_e32 v22, v63, v27
	v_fmac_f32_e32 v23, v64, v27
	v_fmac_f32_e32 v24, v65, v27
	v_fmac_f32_e32 v25, v66, v27
	v_fmac_f32_e32 v26, v67, v27
	v_fma_f32 v27, v68, v27, v7
	v_fmac_f32_e32 v3, v48, v28
	v_fmac_f32_e32 v8, v49, v28
	v_fmac_f32_e32 v9, v50, v28
	v_fmac_f32_e32 v10, v51, v28
	v_fmac_f32_e32 v11, v52, v28
	v_fmac_f32_e32 v12, v53, v28
	v_fmac_f32_e32 v13, v54, v28
	v_fmac_f32_e32 v14, v55, v28
	v_fmac_f32_e32 v15, v56, v28
	v_fmac_f32_e32 v17, v57, v28
	v_fmac_f32_e32 v18, v58, v28
	v_fmac_f32_e32 v19, v59, v28
	v_fmac_f32_e32 v20, v60, v28
	v_fmac_f32_e32 v21, v61, v28
	v_fmac_f32_e32 v22, v62, v28
	v_fmac_f32_e32 v23, v63, v28
	v_fmac_f32_e32 v24, v64, v28
	v_fmac_f32_e32 v25, v65, v28
	v_fmac_f32_e32 v26, v66, v28
	v_fmac_f32_e32 v27, v67, v28
	v_fma_f32 v28, v68, v28, v7
	v_fmac_f32_e32 v3, v46, v29
	v_fmac_f32_e32 v8, v48, v29
	v_fmac_f32_e32 v9, v49, v29
	v_fmac_f32_e32 v10, v50, v29
	v_fmac_f32_e32 v11, v51, v29
	v_fmac_f32_e32 v12, v52, v29
	v_fmac_f32_e32 v13, v53, v29
	v_fmac_f32_e32 v14, v54, v29
	v_fmac_f32_e32 v15, v55, v29
	v_fmac_f32_e32 v17, v56, v29
	v_fmac_f32_e32 v18, v57, v29
	v_fmac_f32_e32 v19, v58, v29
	s_waitcnt vmcnt(0)
; __device__ __forceinline__ float bf2f(bfu h) { return __uint_as_float(((unsigned)h) << 16); }
; __device__ __forceinline__ float sigm(float x) { return 1.f / (1.f + __expf(-x)); }
;   __device__ __forceinline__ bfu* glu() const { return (bfu*)(b + L::o_glu); }
; template <int G>
; __device__ __forceinline__ void p2_conformer(const Params& P, const Ptrs<G>& w, int layer, int item, float* cv, int kslot) {
;     ...
;     for (int sr = 0; sr < 62; ++sr) {
;       const int s = t0 - 30 + sr;
;       float h0 = 0.f;
;       if (s >= 0) {
;         const bfu* gp = w.glu() + (seqbase + s) * 1024 + c;
;         h0 = bf2f(gp[0]) * sigm(bf2f(gp[512]));
;       }
; #pragma unroll
;       for (int tr = 0; tr < 32; ++tr) {
;         const int j = sr - tr;
;         if (j >= 0 && j <= 30) a[tr] += wj[j] * h0;
;       }
;     }
	v_lshlrev_b32_e32 v69, 16, v69
	v_mul_f32_e32 v69, 0xbfb8aa3b, v69
	v_exp_f32_e32 v69, v69
	v_fmac_f32_e32 v20, v59, v29
	v_fmac_f32_e32 v21, v60, v29
	v_fmac_f32_e32 v22, v61, v29
	v_add_f32_e32 v69, 1.0, v69
	v_div_scale_f32 v70, s[72:73], v69, v69, 1.0
	v_rcp_f32_e32 v71, v70
	v_fmac_f32_e32 v23, v62, v29
	v_fmac_f32_e32 v24, v63, v29
	v_fmac_f32_e32 v25, v64, v29
	v_fma_f32 v72, -v70, v71, 1.0
	v_fmac_f32_e32 v71, v72, v71
	v_div_scale_f32 v72, vcc, 1.0, v69, 1.0
	v_mul_f32_e32 v73, v72, v71
	v_fma_f32 v74, -v70, v73, v72
	v_fmac_f32_e32 v73, v74, v71
	v_fma_f32 v70, -v70, v73, v72
	v_div_fmas_f32 v70, v70, v71, v73
	v_div_fixup_f32 v69, v70, v69, 1.0
	global_load_ushort v70, v[4:5], off offset:2048
	v_fmac_f32_e32 v26, v65, v29
	v_fmac_f32_e32 v27, v66, v29
	v_fmac_f32_e32 v28, v67, v29
	v_fma_f32 v29, v68, v29, v7
	v_fmac_f32_e32 v3, v47, v30
	v_fmac_f32_e32 v8, v46, v30
	v_fmac_f32_e32 v9, v48, v30
	v_fmac_f32_e32 v10, v49, v30
	v_fmac_f32_e32 v11, v50, v30
	v_fmac_f32_e32 v12, v51, v30
	v_fmac_f32_e32 v13, v52, v30
	v_fmac_f32_e32 v14, v53, v30
	v_fmac_f32_e32 v15, v54, v30
	v_fmac_f32_e32 v17, v55, v30
	v_fmac_f32_e32 v18, v56, v30
	v_fmac_f32_e32 v19, v57, v30
	v_fmac_f32_e32 v20, v58, v30
	v_fmac_f32_e32 v21, v59, v30
	v_fmac_f32_e32 v22, v60, v30
	v_fmac_f32_e32 v23, v61, v30
	v_fmac_f32_e32 v24, v62, v30
	v_fmac_f32_e32 v25, v63, v30
	v_fmac_f32_e32 v26, v64, v30
	v_fmac_f32_e32 v27, v65, v30
	v_fmac_f32_e32 v28, v66, v30
	v_fmac_f32_e32 v29, v67, v30
	v_fma_f32 v30, v68, v30, v7
	v_fmac_f32_e32 v3, v45, v31
	v_fmac_f32_e32 v8, v47, v31
	v_fmac_f32_e32 v9, v46, v31
	v_fmac_f32_e32 v10, v48, v31
	v_fmac_f32_e32 v11, v49, v31
	v_fmac_f32_e32 v12, v50, v31
	v_fmac_f32_e32 v13, v51, v31
	v_fmac_f32_e32 v14, v52, v31
	v_fmac_f32_e32 v15, v53, v31
	v_fmac_f32_e32 v17, v54, v31
	v_fmac_f32_e32 v18, v55, v31
	v_fmac_f32_e32 v19, v56, v31
	v_fmac_f32_e32 v20, v57, v31
	v_fmac_f32_e32 v21, v58, v31
	v_fmac_f32_e32 v22, v59, v31
	v_fmac_f32_e32 v23, v60, v31
	v_fmac_f32_e32 v24, v61, v31
	v_fmac_f32_e32 v25, v62, v31
	v_fmac_f32_e32 v26, v63, v31
	v_fmac_f32_e32 v27, v64, v31
	v_fmac_f32_e32 v28, v65, v31
	v_fmac_f32_e32 v29, v66, v31
	v_fmac_f32_e32 v30, v67, v31
	v_fma_f32 v31, v68, v31, v7
	v_fmac_f32_e32 v3, v44, v32
	v_fmac_f32_e32 v8, v45, v32
	v_fmac_f32_e32 v9, v47, v32
	v_fmac_f32_e32 v10, v46, v32
	v_fmac_f32_e32 v11, v48, v32
	v_fmac_f32_e32 v12, v49, v32
	v_fmac_f32_e32 v13, v50, v32
	v_fmac_f32_e32 v14, v51, v32
	v_fmac_f32_e32 v15, v52, v32
	v_fmac_f32_e32 v17, v53, v32
	v_fmac_f32_e32 v18, v54, v32
	v_fmac_f32_e32 v19, v55, v32
	v_fmac_f32_e32 v20, v56, v32
	v_fmac_f32_e32 v21, v57, v32
	v_fmac_f32_e32 v22, v58, v32
	v_fmac_f32_e32 v23, v59, v32
	v_fmac_f32_e32 v24, v60, v32
	v_fmac_f32_e32 v25, v61, v32
	v_fmac_f32_e32 v26, v62, v32
	v_fmac_f32_e32 v27, v63, v32
	v_fmac_f32_e32 v28, v64, v32
	v_fmac_f32_e32 v29, v65, v32
	v_fmac_f32_e32 v30, v66, v32
	v_fmac_f32_e32 v31, v67, v32
	v_fma_f32 v32, v68, v32, v7
	v_fmac_f32_e32 v3, v43, v33
	v_fmac_f32_e32 v8, v44, v33
	v_fmac_f32_e32 v9, v45, v33
	v_fmac_f32_e32 v10, v47, v33
	v_fmac_f32_e32 v11, v46, v33
	v_fmac_f32_e32 v12, v48, v33
	v_fmac_f32_e32 v13, v49, v33
	v_fmac_f32_e32 v14, v50, v33
	v_fmac_f32_e32 v15, v51, v33
	v_fmac_f32_e32 v17, v52, v33
	v_fmac_f32_e32 v18, v53, v33
	v_fmac_f32_e32 v19, v54, v33
	v_fmac_f32_e32 v20, v55, v33
	v_fmac_f32_e32 v21, v56, v33
	v_fmac_f32_e32 v22, v57, v33
	v_fmac_f32_e32 v23, v58, v33
	v_fmac_f32_e32 v24, v59, v33
	v_fmac_f32_e32 v25, v60, v33
	v_fmac_f32_e32 v26, v61, v33
	v_fmac_f32_e32 v27, v62, v33
	v_fmac_f32_e32 v28, v63, v33
	v_fmac_f32_e32 v29, v64, v33
	v_fmac_f32_e32 v30, v65, v33
	v_fmac_f32_e32 v31, v66, v33
	v_fmac_f32_e32 v32, v67, v33
	v_fma_f32 v33, v68, v33, v7
	v_fmac_f32_e32 v3, v42, v34
	v_fmac_f32_e32 v8, v43, v34
	v_fmac_f32_e32 v9, v44, v34
	v_fmac_f32_e32 v10, v45, v34
	v_fmac_f32_e32 v11, v47, v34
	v_fmac_f32_e32 v12, v46, v34
	v_fmac_f32_e32 v13, v48, v34
	v_fmac_f32_e32 v14, v49, v34
	v_fmac_f32_e32 v15, v50, v34
	v_fmac_f32_e32 v17, v51, v34
	v_fmac_f32_e32 v18, v52, v34
	v_fmac_f32_e32 v19, v53, v34
	v_fmac_f32_e32 v20, v54, v34
	v_fmac_f32_e32 v21, v55, v34
	v_fmac_f32_e32 v22, v56, v34
	v_fmac_f32_e32 v23, v57, v34
	v_fmac_f32_e32 v24, v58, v34
	v_fmac_f32_e32 v25, v59, v34
	v_fmac_f32_e32 v26, v60, v34
	v_fmac_f32_e32 v27, v61, v34
	v_fmac_f32_e32 v28, v62, v34
	v_fmac_f32_e32 v29, v63, v34
	v_fmac_f32_e32 v30, v64, v34
	v_fmac_f32_e32 v31, v65, v34
	v_fmac_f32_e32 v32, v66, v34
	v_fmac_f32_e32 v33, v67, v34
	v_fma_f32 v34, v68, v34, v7
	v_fmac_f32_e32 v3, v41, v35
	v_fmac_f32_e32 v8, v42, v35
	v_fmac_f32_e32 v9, v43, v35
	v_fmac_f32_e32 v10, v44, v35
	v_fmac_f32_e32 v11, v45, v35
	v_fmac_f32_e32 v12, v47, v35
	v_fmac_f32_e32 v13, v46, v35
	v_fmac_f32_e32 v14, v48, v35
	v_fmac_f32_e32 v15, v49, v35
	v_fmac_f32_e32 v17, v50, v35
	v_fmac_f32_e32 v18, v51, v35
	v_fmac_f32_e32 v19, v52, v35
	v_fmac_f32_e32 v20, v53, v35
	v_fmac_f32_e32 v21, v54, v35
	v_fmac_f32_e32 v22, v55, v35
	v_fmac_f32_e32 v23, v56, v35
	v_fmac_f32_e32 v24, v57, v35
	v_fmac_f32_e32 v25, v58, v35
	v_fmac_f32_e32 v26, v59, v35
	v_fmac_f32_e32 v27, v60, v35
	v_fmac_f32_e32 v28, v61, v35
	v_fmac_f32_e32 v29, v62, v35
	v_fmac_f32_e32 v30, v63, v35
	v_fmac_f32_e32 v31, v64, v35
	v_fmac_f32_e32 v32, v65, v35
	v_fmac_f32_e32 v33, v66, v35
	v_fmac_f32_e32 v34, v67, v35
	v_fma_f32 v35, v68, v35, v7
	v_fmac_f32_e32 v3, v40, v36
	v_fmac_f32_e32 v8, v41, v36
	v_fmac_f32_e32 v9, v42, v36
	v_fmac_f32_e32 v10, v43, v36
	v_fmac_f32_e32 v11, v44, v36
	v_fmac_f32_e32 v12, v45, v36
	v_fmac_f32_e32 v13, v47, v36
	v_fmac_f32_e32 v14, v46, v36
	v_fmac_f32_e32 v15, v48, v36
	v_fmac_f32_e32 v17, v49, v36
	v_fmac_f32_e32 v18, v50, v36
	v_fmac_f32_e32 v19, v51, v36
	v_fmac_f32_e32 v20, v52, v36
	v_fmac_f32_e32 v21, v53, v36
	v_fmac_f32_e32 v22, v54, v36
	v_fmac_f32_e32 v23, v55, v36
	v_fmac_f32_e32 v24, v56, v36
	v_fmac_f32_e32 v25, v57, v36
	v_fmac_f32_e32 v26, v58, v36
	v_fmac_f32_e32 v27, v59, v36
	v_fmac_f32_e32 v28, v60, v36
	v_fmac_f32_e32 v29, v61, v36
	v_fmac_f32_e32 v30, v62, v36
	v_fmac_f32_e32 v31, v63, v36
	v_fmac_f32_e32 v32, v64, v36
	v_fmac_f32_e32 v33, v65, v36
	v_fmac_f32_e32 v34, v66, v36
	v_fmac_f32_e32 v35, v67, v36
	v_fma_f32 v36, v68, v36, v7
	s_waitcnt vmcnt(0)
; __device__ __forceinline__ float bf2f(bfu h) { return __uint_as_float(((unsigned)h) << 16); }
; __device__ __forceinline__ float sigm(float x) { return 1.f / (1.f + __expf(-x)); }
;   __device__ __forceinline__ bfu* glu() const { return (bfu*)(b + L::o_glu); }
; template <int G>
; __device__ __forceinline__ void p2_conformer(const Params& P, const Ptrs<G>& w, int layer, int item, float* cv, int kslot) {
;     ...
;     for (int sr = 0; sr < 62; ++sr) {
;       const int s = t0 - 30 + sr;
;       float h0 = 0.f;
;       if (s >= 0) {
;         const bfu* gp = w.glu() + (seqbase + s) * 1024 + c;
;         h0 = bf2f(gp[0]) * sigm(bf2f(gp[512]));
;       }
; #pragma unroll
;       for (int tr = 0; tr < 32; ++tr) {
;         const int j = sr - tr;
;         if (j >= 0 && j <= 30) a[tr] += wj[j] * h0;
;       }
;     }
	v_lshlrev_b32_e32 v70, 16, v70
	v_fmac_f32_e32 v3, v39, v37
	v_fmac_f32_e32 v8, v40, v37
	v_fmac_f32_e32 v9, v41, v37
	v_fmac_f32_e32 v10, v42, v37
	v_fmac_f32_e32 v11, v43, v37
	v_fmac_f32_e32 v12, v44, v37
	v_fmac_f32_e32 v13, v45, v37
	v_fmac_f32_e32 v14, v47, v37
	v_fmac_f32_e32 v15, v46, v37
	v_fmac_f32_e32 v17, v48, v37
	v_fmac_f32_e32 v18, v49, v37
	v_fmac_f32_e32 v19, v50, v37
	v_fmac_f32_e32 v20, v51, v37
	v_fmac_f32_e32 v21, v52, v37
	v_fmac_f32_e32 v22, v53, v37
	v_fmac_f32_e32 v23, v54, v37
	v_fmac_f32_e32 v24, v55, v37
	v_fmac_f32_e32 v25, v56, v37
	v_fmac_f32_e32 v26, v57, v37
	v_fmac_f32_e32 v27, v58, v37
	v_fmac_f32_e32 v28, v59, v37
	v_fmac_f32_e32 v29, v60, v37
	v_fmac_f32_e32 v30, v61, v37
	v_fmac_f32_e32 v31, v62, v37
	v_fmac_f32_e32 v32, v63, v37
	v_fmac_f32_e32 v33, v64, v37
	v_fmac_f32_e32 v34, v65, v37
	v_fmac_f32_e32 v35, v66, v37
	v_fmac_f32_e32 v36, v67, v37
	v_fma_f32 v37, v68, v37, v7
	v_mul_f32_e32 v69, v69, v70
	s_movk_i32 s17, 0x1000
	v_fmac_f32_e32 v3, v6, v38
	v_fmac_f32_e32 v8, v39, v38
	v_fmac_f32_e32 v9, v40, v38
	v_fmac_f32_e32 v10, v41, v38
	v_fmac_f32_e32 v11, v42, v38
	v_fmac_f32_e32 v12, v43, v38
	v_fmac_f32_e32 v13, v44, v38
	v_fmac_f32_e32 v14, v45, v38
	v_fmac_f32_e32 v15, v47, v38
	v_fmac_f32_e32 v17, v46, v38
	v_fmac_f32_e32 v18, v48, v38
	v_fmac_f32_e32 v19, v49, v38
	v_fmac_f32_e32 v20, v50, v38
	v_fmac_f32_e32 v21, v51, v38
	v_fmac_f32_e32 v22, v52, v38
	v_fmac_f32_e32 v23, v53, v38
	v_fmac_f32_e32 v24, v54, v38
	v_fmac_f32_e32 v25, v55, v38
	v_fmac_f32_e32 v26, v56, v38
	v_fmac_f32_e32 v27, v57, v38
	v_fmac_f32_e32 v28, v58, v38
	v_fmac_f32_e32 v29, v59, v38
	v_fmac_f32_e32 v30, v60, v38
	v_fmac_f32_e32 v31, v61, v38
	v_fmac_f32_e32 v32, v62, v38
	v_fmac_f32_e32 v33, v63, v38
	v_fmac_f32_e32 v34, v64, v38
	v_fmac_f32_e32 v35, v65, v38
	v_fmac_f32_e32 v36, v66, v38
	v_fmac_f32_e32 v37, v67, v38
	v_fma_f32 v38, v68, v38, v7
	v_fmac_f32_e32 v7, v68, v69
	v_add_co_u32_e32 v68, vcc, s17, v4
	v_fmac_f32_e32 v8, v6, v69
	v_fmac_f32_e32 v9, v39, v69
	v_fmac_f32_e32 v10, v40, v69
	v_fmac_f32_e32 v11, v41, v69
	v_fmac_f32_e32 v12, v42, v69
	v_fmac_f32_e32 v13, v43, v69
	v_fmac_f32_e32 v14, v44, v69
	v_fmac_f32_e32 v15, v45, v69
	v_fmac_f32_e32 v17, v47, v69
	v_fmac_f32_e32 v18, v46, v69
	v_fmac_f32_e32 v19, v48, v69
	v_fmac_f32_e32 v20, v49, v69
	v_fmac_f32_e32 v21, v50, v69
	v_fmac_f32_e32 v22, v51, v69
	v_fmac_f32_e32 v23, v52, v69
	v_fmac_f32_e32 v24, v53, v69
	v_fmac_f32_e32 v25, v54, v69
	v_fmac_f32_e32 v26, v55, v69
	v_fmac_f32_e32 v27, v56, v69
	v_fmac_f32_e32 v28, v57, v69
	v_fmac_f32_e32 v29, v58, v69
	v_fmac_f32_e32 v30, v59, v69
	v_fmac_f32_e32 v31, v60, v69
	v_fmac_f32_e32 v32, v61, v69
	v_fmac_f32_e32 v33, v62, v69
	v_fmac_f32_e32 v34, v63, v69
	v_fmac_f32_e32 v35, v64, v69
	v_fmac_f32_e32 v36, v65, v69
	v_fmac_f32_e32 v37, v66, v69
	v_fmac_f32_e32 v38, v67, v69
	v_addc_co_u32_e32 v69, vcc, 0, v5, vcc
	global_load_ushort v70, v[68:69], off offset:1024
	s_movk_i32 s17, 0x2000
	s_xor_b64 s[10:11], s[92:93], -1
	s_mov_b32 s92, 0xf000
	v_lshlrev_b32_e32 v2, 2, v2
	s_waitcnt vmcnt(0)
	v_lshlrev_b32_e32 v70, 16, v70
	v_mul_f32_e32 v70, 0xbfb8aa3b, v70
	v_exp_f32_e32 v70, v70
	s_nop 0
	v_add_f32_e32 v70, 1.0, v70
	v_div_scale_f32 v71, s[72:73], v70, v70, 1.0
	v_rcp_f32_e32 v72, v71
	s_nop 0
	v_fma_f32 v73, -v71, v72, 1.0
	v_fmac_f32_e32 v72, v73, v72
	v_div_scale_f32 v73, vcc, 1.0, v70, 1.0
	v_mul_f32_e32 v74, v73, v72
	v_fma_f32 v75, -v71, v74, v73
	v_fmac_f32_e32 v74, v75, v72
	v_fma_f32 v71, -v71, v74, v73
	v_div_fmas_f32 v71, v71, v72, v74
	v_div_fixup_f32 v72, v71, v70, 1.0
	v_add_co_u32_e32 v70, vcc, s17, v4
	s_movk_i32 s17, 0x3000
	s_nop 0
	v_addc_co_u32_e32 v71, vcc, 0, v5, vcc
	global_load_ushort v73, v[70:71], off offset:-4096
	s_waitcnt vmcnt(0)
	v_lshlrev_b32_e32 v73, 16, v73
	v_mul_f32_e32 v72, v72, v73
	v_fmac_f32_e32 v7, v67, v72
	global_load_ushort v67, v[68:69], off offset:3072
	v_fmac_f32_e32 v9, v6, v72
	global_load_ushort v68, v[68:69], off offset:2048
	v_fmac_f32_e32 v10, v39, v72
	v_fmac_f32_e32 v11, v40, v72
	v_fmac_f32_e32 v12, v41, v72
	v_fmac_f32_e32 v13, v42, v72
	v_fmac_f32_e32 v14, v43, v72
	v_fmac_f32_e32 v15, v44, v72
	v_fmac_f32_e32 v17, v45, v72
	v_fmac_f32_e32 v18, v47, v72
	v_fmac_f32_e32 v19, v46, v72
	v_fmac_f32_e32 v20, v48, v72
	v_fmac_f32_e32 v21, v49, v72
	v_fmac_f32_e32 v22, v50, v72
	v_fmac_f32_e32 v23, v51, v72
	v_fmac_f32_e32 v24, v52, v72
	v_fmac_f32_e32 v25, v53, v72
	v_fmac_f32_e32 v26, v54, v72
	v_fmac_f32_e32 v27, v55, v72
	v_fmac_f32_e32 v28, v56, v72
	v_fmac_f32_e32 v29, v57, v72
	v_fmac_f32_e32 v30, v58, v72
	v_fmac_f32_e32 v31, v59, v72
	v_fmac_f32_e32 v32, v60, v72
	v_fmac_f32_e32 v33, v61, v72
	v_fmac_f32_e32 v34, v62, v72
	v_fmac_f32_e32 v35, v63, v72
	v_fmac_f32_e32 v36, v64, v72
	v_fmac_f32_e32 v37, v65, v72
	v_fmac_f32_e32 v38, v66, v72
	s_waitcnt vmcnt(1)
	v_lshlrev_b32_e32 v67, 16, v67
	v_mul_f32_e32 v67, 0xbfb8aa3b, v67
	v_exp_f32_e32 v67, v67
	s_waitcnt vmcnt(0)
; __device__ __forceinline__ float bf2f(bfu h) { return __uint_as_float(((unsigned)h) << 16); }
; __device__ __forceinline__ float sigm(float x) { return 1.f / (1.f + __expf(-x)); }
;   __device__ __forceinline__ bfu* glu() const { return (bfu*)(b + L::o_glu); }
; template <int G>
; __device__ __forceinline__ void p2_conformer(const Params& P, const Ptrs<G>& w, int layer, int item, float* cv, int kslot) {
;     ...
;     for (int sr = 0; sr < 62; ++sr) {
;       const int s = t0 - 30 + sr;
;       float h0 = 0.f;
;       if (s >= 0) {
;         const bfu* gp = w.glu() + (seqbase + s) * 1024 + c;
;         h0 = bf2f(gp[0]) * sigm(bf2f(gp[512]));
;       }
; #pragma unroll
;       for (int tr = 0; tr < 32; ++tr) {
;         const int j = sr - tr;
;         if (j >= 0 && j <= 30) a[tr] += wj[j] * h0;
;       }
;     }
	v_lshlrev_b32_e32 v68, 16, v68
	v_add_f32_e32 v67, 1.0, v67
	v_div_scale_f32 v72, s[72:73], v67, v67, 1.0
	v_rcp_f32_e32 v73, v72
	s_nop 0
	v_fma_f32 v74, -v72, v73, 1.0
	v_fmac_f32_e32 v73, v74, v73
	v_div_scale_f32 v74, vcc, 1.0, v67, 1.0
	v_mul_f32_e32 v75, v74, v73
	v_fma_f32 v76, -v72, v75, v74
	v_fmac_f32_e32 v75, v76, v73
	v_fma_f32 v72, -v72, v75, v74
	v_div_fmas_f32 v72, v72, v73, v75
	v_div_fixup_f32 v67, v72, v67, 1.0
	v_mul_f32_e32 v67, v67, v68
	v_fmac_f32_e32 v7, v66, v67
	global_load_ushort v66, v[70:71], off offset:1024
	v_fmac_f32_e32 v10, v6, v67
	v_fmac_f32_e32 v11, v39, v67
	v_fmac_f32_e32 v12, v40, v67
	v_fmac_f32_e32 v13, v41, v67
	v_fmac_f32_e32 v14, v42, v67
	v_fmac_f32_e32 v15, v43, v67
	v_fmac_f32_e32 v17, v44, v67
	v_fmac_f32_e32 v18, v45, v67
	v_fmac_f32_e32 v19, v47, v67
	v_fmac_f32_e32 v20, v46, v67
	v_fmac_f32_e32 v21, v48, v67
	v_fmac_f32_e32 v22, v49, v67
	v_fmac_f32_e32 v23, v50, v67
	v_fmac_f32_e32 v24, v51, v67
	v_fmac_f32_e32 v25, v52, v67
	v_fmac_f32_e32 v26, v53, v67
	v_fmac_f32_e32 v27, v54, v67
	v_fmac_f32_e32 v28, v55, v67
	v_fmac_f32_e32 v29, v56, v67
	v_fmac_f32_e32 v30, v57, v67
	v_fmac_f32_e32 v31, v58, v67
	v_fmac_f32_e32 v32, v59, v67
	v_fmac_f32_e32 v33, v60, v67
	v_fmac_f32_e32 v34, v61, v67
	v_fmac_f32_e32 v35, v62, v67
	v_fmac_f32_e32 v36, v63, v67
	v_fmac_f32_e32 v37, v64, v67
	v_fmac_f32_e32 v38, v65, v67
	s_waitcnt vmcnt(0)
	v_lshlrev_b32_e32 v66, 16, v66
	v_mul_f32_e32 v66, 0xbfb8aa3b, v66
	v_exp_f32_e32 v66, v66
	s_nop 0
	v_add_f32_e32 v66, 1.0, v66
	v_div_scale_f32 v67, s[72:73], v66, v66, 1.0
	v_rcp_f32_e32 v68, v67
	s_nop 0
	v_fma_f32 v69, -v67, v68, 1.0
	v_fmac_f32_e32 v68, v69, v68
	v_div_scale_f32 v69, vcc, 1.0, v66, 1.0
	v_mul_f32_e32 v72, v69, v68
	v_fma_f32 v73, -v67, v72, v69
	v_fmac_f32_e32 v72, v73, v68
	v_fma_f32 v67, -v67, v72, v69
	v_div_fmas_f32 v67, v67, v68, v72
	v_div_fixup_f32 v66, v67, v66, 1.0
	global_load_ushort v67, v[70:71], off
	s_waitcnt vmcnt(0)
	v_lshlrev_b32_e32 v67, 16, v67
	v_mul_f32_e32 v66, v66, v67
	v_fmac_f32_e32 v7, v65, v66
	global_load_ushort v65, v[70:71], off offset:3072
	v_fmac_f32_e32 v11, v6, v66
	v_fmac_f32_e32 v12, v39, v66
	v_fmac_f32_e32 v13, v40, v66
	v_fmac_f32_e32 v14, v41, v66
	v_fmac_f32_e32 v15, v42, v66
	v_fmac_f32_e32 v17, v43, v66
	v_fmac_f32_e32 v18, v44, v66
	v_fmac_f32_e32 v19, v45, v66
	v_fmac_f32_e32 v20, v47, v66
	v_fmac_f32_e32 v21, v46, v66
	v_fmac_f32_e32 v22, v48, v66
	v_fmac_f32_e32 v23, v49, v66
	v_fmac_f32_e32 v24, v50, v66
	v_fmac_f32_e32 v25, v51, v66
	v_fmac_f32_e32 v26, v52, v66
	v_fmac_f32_e32 v27, v53, v66
	v_fmac_f32_e32 v28, v54, v66
	v_fmac_f32_e32 v29, v55, v66
	v_fmac_f32_e32 v30, v56, v66
	v_fmac_f32_e32 v31, v57, v66
	v_fmac_f32_e32 v32, v58, v66
	v_fmac_f32_e32 v33, v59, v66
	v_fmac_f32_e32 v34, v60, v66
	v_fmac_f32_e32 v35, v61, v66
	v_fmac_f32_e32 v36, v62, v66
	v_fmac_f32_e32 v37, v63, v66
	v_fmac_f32_e32 v38, v64, v66
	s_waitcnt vmcnt(0)
	v_lshlrev_b32_e32 v65, 16, v65
	v_mul_f32_e32 v65, 0xbfb8aa3b, v65
	v_exp_f32_e32 v65, v65
	s_nop 0
	v_add_f32_e32 v65, 1.0, v65
	v_div_scale_f32 v66, s[72:73], v65, v65, 1.0
	v_rcp_f32_e32 v67, v66
	s_nop 0
	v_fma_f32 v68, -v66, v67, 1.0
	v_fmac_f32_e32 v67, v68, v67
	v_div_scale_f32 v68, vcc, 1.0, v65, 1.0
	v_mul_f32_e32 v69, v68, v67
	v_fma_f32 v72, -v66, v69, v68
	v_fmac_f32_e32 v69, v72, v67
	v_fma_f32 v66, -v66, v69, v68
	v_div_fmas_f32 v66, v66, v67, v69
	v_div_fixup_f32 v65, v66, v65, 1.0
	global_load_ushort v66, v[70:71], off offset:2048
	s_waitcnt vmcnt(0)
	v_lshlrev_b32_e32 v66, 16, v66
	v_mul_f32_e32 v65, v65, v66
	v_fmac_f32_e32 v7, v64, v65
	v_add_co_u32_e32 v64, vcc, s17, v4
	v_fmac_f32_e32 v12, v6, v65
	v_fmac_f32_e32 v13, v39, v65
	v_fmac_f32_e32 v14, v40, v65
	v_fmac_f32_e32 v15, v41, v65
	v_fmac_f32_e32 v17, v42, v65
	v_fmac_f32_e32 v18, v43, v65
	v_fmac_f32_e32 v19, v44, v65
	v_fmac_f32_e32 v20, v45, v65
	v_fmac_f32_e32 v21, v47, v65
	v_fmac_f32_e32 v22, v46, v65
	v_fmac_f32_e32 v23, v48, v65
	v_fmac_f32_e32 v24, v49, v65
	v_fmac_f32_e32 v25, v50, v65
	v_fmac_f32_e32 v26, v51, v65
	v_fmac_f32_e32 v27, v52, v65
	v_fmac_f32_e32 v28, v53, v65
	v_fmac_f32_e32 v29, v54, v65
	v_fmac_f32_e32 v30, v55, v65
	v_fmac_f32_e32 v31, v56, v65
	v_fmac_f32_e32 v32, v57, v65
	v_fmac_f32_e32 v33, v58, v65
	v_fmac_f32_e32 v34, v59, v65
	v_fmac_f32_e32 v35, v60, v65
	v_fmac_f32_e32 v36, v61, v65
	v_fmac_f32_e32 v37, v62, v65
	v_fmac_f32_e32 v38, v63, v65
	v_addc_co_u32_e32 v65, vcc, 0, v5, vcc
	global_load_ushort v66, v[64:65], off offset:1024
	s_movk_i32 s17, 0x4000
	s_waitcnt vmcnt(0)
	v_lshlrev_b32_e32 v66, 16, v66
	v_mul_f32_e32 v66, 0xbfb8aa3b, v66
	v_exp_f32_e32 v66, v66
	s_nop 0
	v_add_f32_e32 v66, 1.0, v66
	v_div_scale_f32 v67, s[72:73], v66, v66, 1.0
	v_rcp_f32_e32 v68, v67
	s_nop 0
	v_fma_f32 v69, -v67, v68, 1.0
	v_fmac_f32_e32 v68, v69, v68
	v_div_scale_f32 v69, vcc, 1.0, v66, 1.0
	v_mul_f32_e32 v70, v69, v68
	v_fma_f32 v71, -v67, v70, v69
	v_fmac_f32_e32 v70, v71, v68
	v_fma_f32 v67, -v67, v70, v69
	v_div_fmas_f32 v67, v67, v68, v70
	v_div_fixup_f32 v68, v67, v66, 1.0
	v_add_co_u32_e32 v66, vcc, s17, v4
	s_nop 1
	v_addc_co_u32_e32 v67, vcc, 0, v5, vcc
	global_load_ushort v69, v[66:67], off offset:-4096
	s_waitcnt vmcnt(0)
; __device__ __forceinline__ float bf2f(bfu h) { return __uint_as_float(((unsigned)h) << 16); }
; __device__ __forceinline__ float sigm(float x) { return 1.f / (1.f + __expf(-x)); }
;   __device__ __forceinline__ bfu* glu() const { return (bfu*)(b + L::o_glu); }
; template <int G>
; __device__ __forceinline__ void p2_conformer(const Params& P, const Ptrs<G>& w, int layer, int item, float* cv, int kslot) {
;     ...
;     for (int sr = 0; sr < 62; ++sr) {
;       const int s = t0 - 30 + sr;
;       float h0 = 0.f;
;       if (s >= 0) {
;         const bfu* gp = w.glu() + (seqbase + s) * 1024 + c;
;         h0 = bf2f(gp[0]) * sigm(bf2f(gp[512]));
;       }
; #pragma unroll
;       for (int tr = 0; tr < 32; ++tr) {
;         const int j = sr - tr;
;         if (j >= 0 && j <= 30) a[tr] += wj[j] * h0;
;       }
;     }
	v_lshlrev_b32_e32 v69, 16, v69
	v_mul_f32_e32 v68, v68, v69
	v_fmac_f32_e32 v7, v63, v68
	global_load_ushort v63, v[64:65], off offset:3072
	v_fmac_f32_e32 v13, v6, v68
	global_load_ushort v64, v[64:65], off offset:2048
	v_fmac_f32_e32 v14, v39, v68
	v_fmac_f32_e32 v15, v40, v68
	v_fmac_f32_e32 v17, v41, v68
	v_fmac_f32_e32 v18, v42, v68
	v_fmac_f32_e32 v19, v43, v68
	v_fmac_f32_e32 v20, v44, v68
	v_fmac_f32_e32 v21, v45, v68
	v_fmac_f32_e32 v22, v47, v68
	v_fmac_f32_e32 v23, v46, v68
	v_fmac_f32_e32 v24, v48, v68
	v_fmac_f32_e32 v25, v49, v68
	v_fmac_f32_e32 v26, v50, v68
	v_fmac_f32_e32 v27, v51, v68
	v_fmac_f32_e32 v28, v52, v68
	v_fmac_f32_e32 v29, v53, v68
	v_fmac_f32_e32 v30, v54, v68
	v_fmac_f32_e32 v31, v55, v68
	v_fmac_f32_e32 v32, v56, v68
	v_fmac_f32_e32 v33, v57, v68
	v_fmac_f32_e32 v34, v58, v68
	v_fmac_f32_e32 v35, v59, v68
	v_fmac_f32_e32 v36, v60, v68
	v_fmac_f32_e32 v37, v61, v68
	v_fmac_f32_e32 v38, v62, v68
	s_waitcnt vmcnt(1)
	v_lshlrev_b32_e32 v63, 16, v63
	v_mul_f32_e32 v63, 0xbfb8aa3b, v63
	v_exp_f32_e32 v63, v63
	s_waitcnt vmcnt(0)
	v_lshlrev_b32_e32 v64, 16, v64
	v_add_f32_e32 v63, 1.0, v63
	v_div_scale_f32 v68, s[72:73], v63, v63, 1.0
	v_rcp_f32_e32 v69, v68
	s_nop 0
	v_fma_f32 v70, -v68, v69, 1.0
	v_fmac_f32_e32 v69, v70, v69
	v_div_scale_f32 v70, vcc, 1.0, v63, 1.0
	v_mul_f32_e32 v71, v70, v69
	v_fma_f32 v72, -v68, v71, v70
	v_fmac_f32_e32 v71, v72, v69
	v_fma_f32 v68, -v68, v71, v70
	v_div_fmas_f32 v68, v68, v69, v71
	v_div_fixup_f32 v63, v68, v63, 1.0
	v_mul_f32_e32 v63, v63, v64
	v_fmac_f32_e32 v7, v62, v63
	global_load_ushort v62, v[66:67], off offset:1024
	v_fmac_f32_e32 v14, v6, v63
	v_fmac_f32_e32 v15, v39, v63
	v_fmac_f32_e32 v17, v40, v63
	v_fmac_f32_e32 v18, v41, v63
	v_fmac_f32_e32 v19, v42, v63
	v_fmac_f32_e32 v20, v43, v63
	v_fmac_f32_e32 v21, v44, v63
	v_fmac_f32_e32 v22, v45, v63
	v_fmac_f32_e32 v23, v47, v63
	v_fmac_f32_e32 v24, v46, v63
	v_fmac_f32_e32 v25, v48, v63
	v_fmac_f32_e32 v26, v49, v63
	v_fmac_f32_e32 v27, v50, v63
	v_fmac_f32_e32 v28, v51, v63
	v_fmac_f32_e32 v29, v52, v63
	v_fmac_f32_e32 v30, v53, v63
	v_fmac_f32_e32 v31, v54, v63
	v_fmac_f32_e32 v32, v55, v63
	v_fmac_f32_e32 v33, v56, v63
	v_fmac_f32_e32 v34, v57, v63
	v_fmac_f32_e32 v35, v58, v63
	v_fmac_f32_e32 v36, v59, v63
	v_fmac_f32_e32 v37, v60, v63
	v_fmac_f32_e32 v38, v61, v63
	s_waitcnt vmcnt(0)
	v_lshlrev_b32_e32 v62, 16, v62
	v_mul_f32_e32 v62, 0xbfb8aa3b, v62
	v_exp_f32_e32 v62, v62
	s_nop 0
	v_add_f32_e32 v62, 1.0, v62
	v_div_scale_f32 v63, s[72:73], v62, v62, 1.0
	v_rcp_f32_e32 v64, v63
	s_nop 0
	v_fma_f32 v65, -v63, v64, 1.0
	v_fmac_f32_e32 v64, v65, v64
	v_div_scale_f32 v65, vcc, 1.0, v62, 1.0
	v_mul_f32_e32 v68, v65, v64
	v_fma_f32 v69, -v63, v68, v65
	v_fmac_f32_e32 v68, v69, v64
	v_fma_f32 v63, -v63, v68, v65
	v_div_fmas_f32 v63, v63, v64, v68
	v_div_fixup_f32 v62, v63, v62, 1.0
	global_load_ushort v63, v[66:67], off
	s_waitcnt vmcnt(0)
	v_lshlrev_b32_e32 v63, 16, v63
	v_mul_f32_e32 v62, v62, v63
	v_fmac_f32_e32 v7, v61, v62
	global_load_ushort v61, v[66:67], off offset:3072
	v_fmac_f32_e32 v15, v6, v62
	v_fmac_f32_e32 v17, v39, v62
	v_fmac_f32_e32 v18, v40, v62
	v_fmac_f32_e32 v19, v41, v62
	v_fmac_f32_e32 v20, v42, v62
	v_fmac_f32_e32 v21, v43, v62
	v_fmac_f32_e32 v22, v44, v62
	v_fmac_f32_e32 v23, v45, v62
	v_fmac_f32_e32 v24, v47, v62
	v_fmac_f32_e32 v25, v46, v62
	v_fmac_f32_e32 v26, v48, v62
	v_fmac_f32_e32 v27, v49, v62
	v_fmac_f32_e32 v28, v50, v62
	v_fmac_f32_e32 v29, v51, v62
	v_fmac_f32_e32 v30, v52, v62
	v_fmac_f32_e32 v31, v53, v62
	v_fmac_f32_e32 v32, v54, v62
	v_fmac_f32_e32 v33, v55, v62
	v_fmac_f32_e32 v34, v56, v62
	v_fmac_f32_e32 v35, v57, v62
	v_fmac_f32_e32 v36, v58, v62
	v_fmac_f32_e32 v37, v59, v62
	v_fmac_f32_e32 v38, v60, v62
	s_waitcnt vmcnt(0)
	v_lshlrev_b32_e32 v61, 16, v61
	v_mul_f32_e32 v61, 0xbfb8aa3b, v61
	v_exp_f32_e32 v61, v61
	s_nop 0
	v_add_f32_e32 v61, 1.0, v61
	v_div_scale_f32 v62, s[72:73], v61, v61, 1.0
	v_rcp_f32_e32 v63, v62
	s_movk_i32 s72, 0x5000
	v_fma_f32 v64, -v62, v63, 1.0
	v_fmac_f32_e32 v63, v64, v63
	v_div_scale_f32 v64, vcc, 1.0, v61, 1.0
	v_mul_f32_e32 v65, v64, v63
	v_fma_f32 v68, -v62, v65, v64
	v_fmac_f32_e32 v65, v68, v63
	v_fma_f32 v62, -v62, v65, v64
	v_div_fmas_f32 v62, v62, v63, v65
	v_div_fixup_f32 v61, v62, v61, 1.0
	global_load_ushort v62, v[66:67], off offset:2048
	s_waitcnt vmcnt(0)
	v_lshlrev_b32_e32 v62, 16, v62
	v_mul_f32_e32 v61, v61, v62
	v_fmac_f32_e32 v7, v60, v61
	v_add_co_u32_e32 v60, vcc, s72, v4
	v_fmac_f32_e32 v17, v6, v61
	v_fmac_f32_e32 v18, v39, v61
	v_fmac_f32_e32 v19, v40, v61
	v_fmac_f32_e32 v20, v41, v61
	v_fmac_f32_e32 v21, v42, v61
	v_fmac_f32_e32 v22, v43, v61
	v_fmac_f32_e32 v23, v44, v61
	v_fmac_f32_e32 v24, v45, v61
	v_fmac_f32_e32 v25, v47, v61
	v_fmac_f32_e32 v26, v46, v61
	v_fmac_f32_e32 v27, v48, v61
	v_fmac_f32_e32 v28, v49, v61
	v_fmac_f32_e32 v29, v50, v61
	v_fmac_f32_e32 v30, v51, v61
	v_fmac_f32_e32 v31, v52, v61
	v_fmac_f32_e32 v32, v53, v61
	v_fmac_f32_e32 v33, v54, v61
	v_fmac_f32_e32 v34, v55, v61
	v_fmac_f32_e32 v35, v56, v61
	v_fmac_f32_e32 v36, v57, v61
	v_fmac_f32_e32 v37, v58, v61
	v_fmac_f32_e32 v38, v59, v61
	v_addc_co_u32_e32 v61, vcc, 0, v5, vcc
	global_load_ushort v62, v[60:61], off offset:1024
	s_waitcnt vmcnt(0)
	v_lshlrev_b32_e32 v62, 16, v62
	v_mul_f32_e32 v62, 0xbfb8aa3b, v62
	v_exp_f32_e32 v62, v62
	s_nop 0
	v_add_f32_e32 v62, 1.0, v62
	v_div_scale_f32 v63, s[72:73], v62, v62, 1.0
	v_rcp_f32_e32 v64, v63
	s_nop 0
	v_fma_f32 v65, -v63, v64, 1.0
	v_fmac_f32_e32 v64, v65, v64
	v_div_scale_f32 v65, vcc, 1.0, v62, 1.0
	v_mul_f32_e32 v66, v65, v64
	v_fma_f32 v67, -v63, v66, v65
	v_fmac_f32_e32 v66, v67, v64
	v_fma_f32 v63, -v63, v66, v65
	v_div_fmas_f32 v63, v63, v64, v66
	v_div_fixup_f32 v64, v63, v62, 1.0
	v_add_co_u32_e32 v62, vcc, s16, v4
	s_nop 1
	v_addc_co_u32_e32 v63, vcc, 0, v5, vcc
	global_load_ushort v65, v[62:63], off offset:-4096
	s_waitcnt vmcnt(0)
; __device__ __forceinline__ float bf2f(bfu h) { return __uint_as_float(((unsigned)h) << 16); }
; __device__ __forceinline__ float sigm(float x) { return 1.f / (1.f + __expf(-x)); }
;   __device__ __forceinline__ bfu* glu() const { return (bfu*)(b + L::o_glu); }
; template <int G>
; __device__ __forceinline__ void p2_conformer(const Params& P, const Ptrs<G>& w, int layer, int item, float* cv, int kslot) {
;     ...
;     for (int sr = 0; sr < 62; ++sr) {
;       const int s = t0 - 30 + sr;
;       float h0 = 0.f;
;       if (s >= 0) {
;         const bfu* gp = w.glu() + (seqbase + s) * 1024 + c;
;         h0 = bf2f(gp[0]) * sigm(bf2f(gp[512]));
;       }
; #pragma unroll
;       for (int tr = 0; tr < 32; ++tr) {
;         const int j = sr - tr;
;         if (j >= 0 && j <= 30) a[tr] += wj[j] * h0;
;       }
;     }
	v_lshlrev_b32_e32 v65, 16, v65
	v_mul_f32_e32 v64, v64, v65
	v_fmac_f32_e32 v7, v59, v64
	global_load_ushort v59, v[60:61], off offset:3072
	v_fmac_f32_e32 v18, v6, v64
	global_load_ushort v60, v[60:61], off offset:2048
	v_fmac_f32_e32 v19, v39, v64
	v_fmac_f32_e32 v20, v40, v64
	v_fmac_f32_e32 v21, v41, v64
	v_fmac_f32_e32 v22, v42, v64
	v_fmac_f32_e32 v23, v43, v64
	v_fmac_f32_e32 v24, v44, v64
	v_fmac_f32_e32 v25, v45, v64
	v_fmac_f32_e32 v26, v47, v64
	v_fmac_f32_e32 v27, v46, v64
	v_fmac_f32_e32 v28, v48, v64
	v_fmac_f32_e32 v29, v49, v64
	v_fmac_f32_e32 v30, v50, v64
	v_fmac_f32_e32 v31, v51, v64
	v_fmac_f32_e32 v32, v52, v64
	v_fmac_f32_e32 v33, v53, v64
	v_fmac_f32_e32 v34, v54, v64
	v_fmac_f32_e32 v35, v55, v64
	v_fmac_f32_e32 v36, v56, v64
	v_fmac_f32_e32 v37, v57, v64
	v_fmac_f32_e32 v38, v58, v64
	s_waitcnt vmcnt(1)
	v_lshlrev_b32_e32 v59, 16, v59
	v_mul_f32_e32 v59, 0xbfb8aa3b, v59
	v_exp_f32_e32 v59, v59
	s_waitcnt vmcnt(0)
	v_lshlrev_b32_e32 v60, 16, v60
	v_add_f32_e32 v59, 1.0, v59
	v_div_scale_f32 v64, s[72:73], v59, v59, 1.0
	v_rcp_f32_e32 v65, v64
	s_nop 0
	v_fma_f32 v66, -v64, v65, 1.0
	v_fmac_f32_e32 v65, v66, v65
	v_div_scale_f32 v66, vcc, 1.0, v59, 1.0
	v_mul_f32_e32 v67, v66, v65
	v_fma_f32 v68, -v64, v67, v66
	v_fmac_f32_e32 v67, v68, v65
	v_fma_f32 v64, -v64, v67, v66
	v_div_fmas_f32 v64, v64, v65, v67
	v_div_fixup_f32 v59, v64, v59, 1.0
	v_mul_f32_e32 v59, v59, v60
	v_fmac_f32_e32 v7, v58, v59
	global_load_ushort v58, v[62:63], off offset:1024
	v_fmac_f32_e32 v19, v6, v59
	v_fmac_f32_e32 v20, v39, v59
	v_fmac_f32_e32 v21, v40, v59
	v_fmac_f32_e32 v22, v41, v59
	v_fmac_f32_e32 v23, v42, v59
	v_fmac_f32_e32 v24, v43, v59
	v_fmac_f32_e32 v25, v44, v59
	v_fmac_f32_e32 v26, v45, v59
	v_fmac_f32_e32 v27, v47, v59
	v_fmac_f32_e32 v28, v46, v59
	v_fmac_f32_e32 v29, v48, v59
	v_fmac_f32_e32 v30, v49, v59
	v_fmac_f32_e32 v31, v50, v59
	v_fmac_f32_e32 v32, v51, v59
	v_fmac_f32_e32 v33, v52, v59
	v_fmac_f32_e32 v34, v53, v59
	v_fmac_f32_e32 v35, v54, v59
	v_fmac_f32_e32 v36, v55, v59
	v_fmac_f32_e32 v37, v56, v59
	v_fmac_f32_e32 v38, v57, v59
	s_waitcnt vmcnt(0)
	v_lshlrev_b32_e32 v58, 16, v58
	v_mul_f32_e32 v58, 0xbfb8aa3b, v58
	v_exp_f32_e32 v58, v58
	s_nop 0
	v_add_f32_e32 v58, 1.0, v58
	v_div_scale_f32 v59, s[72:73], v58, v58, 1.0
	v_rcp_f32_e32 v60, v59
	s_nop 0
	v_fma_f32 v61, -v59, v60, 1.0
	v_fmac_f32_e32 v60, v61, v60
	v_div_scale_f32 v61, vcc, 1.0, v58, 1.0
	v_mul_f32_e32 v64, v61, v60
	v_fma_f32 v65, -v59, v64, v61
	v_fmac_f32_e32 v64, v65, v60
	v_fma_f32 v59, -v59, v64, v61
	v_div_fmas_f32 v59, v59, v60, v64
	v_div_fixup_f32 v58, v59, v58, 1.0
	global_load_ushort v59, v[62:63], off
	s_waitcnt vmcnt(0)
	v_lshlrev_b32_e32 v59, 16, v59
	v_mul_f32_e32 v58, v58, v59
	v_fmac_f32_e32 v7, v57, v58
	global_load_ushort v57, v[62:63], off offset:3072
	v_fmac_f32_e32 v20, v6, v58
	v_fmac_f32_e32 v21, v39, v58
	v_fmac_f32_e32 v22, v40, v58
	v_fmac_f32_e32 v23, v41, v58
	v_fmac_f32_e32 v24, v42, v58
	v_fmac_f32_e32 v25, v43, v58
	v_fmac_f32_e32 v26, v44, v58
	v_fmac_f32_e32 v27, v45, v58
	v_fmac_f32_e32 v28, v47, v58
	v_fmac_f32_e32 v29, v46, v58
	v_fmac_f32_e32 v30, v48, v58
	v_fmac_f32_e32 v31, v49, v58
	v_fmac_f32_e32 v32, v50, v58
	v_fmac_f32_e32 v33, v51, v58
	v_fmac_f32_e32 v34, v52, v58
	v_fmac_f32_e32 v35, v53, v58
	v_fmac_f32_e32 v36, v54, v58
	v_fmac_f32_e32 v37, v55, v58
	v_fmac_f32_e32 v38, v56, v58
	s_waitcnt vmcnt(0)
	v_lshlrev_b32_e32 v57, 16, v57
	v_mul_f32_e32 v57, 0xbfb8aa3b, v57
	v_exp_f32_e32 v57, v57
	s_nop 0
	v_add_f32_e32 v57, 1.0, v57
	v_div_scale_f32 v58, s[72:73], v57, v57, 1.0
	v_rcp_f32_e32 v59, v58
	s_movk_i32 s72, 0x7000
	v_fma_f32 v60, -v58, v59, 1.0
	v_fmac_f32_e32 v59, v60, v59
	v_div_scale_f32 v60, vcc, 1.0, v57, 1.0
	v_mul_f32_e32 v61, v60, v59
	v_fma_f32 v64, -v58, v61, v60
	v_fmac_f32_e32 v61, v64, v59
	v_fma_f32 v58, -v58, v61, v60
	v_div_fmas_f32 v58, v58, v59, v61
	v_div_fixup_f32 v57, v58, v57, 1.0
	global_load_ushort v58, v[62:63], off offset:2048
	s_waitcnt vmcnt(0)
	v_lshlrev_b32_e32 v58, 16, v58
	v_mul_f32_e32 v57, v57, v58
	v_fmac_f32_e32 v7, v56, v57
	v_add_co_u32_e32 v56, vcc, s72, v4
	v_fmac_f32_e32 v21, v6, v57
	v_fmac_f32_e32 v22, v39, v57
	v_fmac_f32_e32 v23, v40, v57
	v_fmac_f32_e32 v24, v41, v57
	v_fmac_f32_e32 v25, v42, v57
	v_fmac_f32_e32 v26, v43, v57
	v_fmac_f32_e32 v27, v44, v57
	v_fmac_f32_e32 v28, v45, v57
	v_fmac_f32_e32 v29, v47, v57
	v_fmac_f32_e32 v30, v46, v57
	v_fmac_f32_e32 v31, v48, v57
	v_fmac_f32_e32 v32, v49, v57
	v_fmac_f32_e32 v33, v50, v57
	v_fmac_f32_e32 v34, v51, v57
	v_fmac_f32_e32 v35, v52, v57
	v_fmac_f32_e32 v36, v53, v57
	v_fmac_f32_e32 v37, v54, v57
	v_fmac_f32_e32 v38, v55, v57
	v_addc_co_u32_e32 v57, vcc, 0, v5, vcc
	global_load_ushort v58, v[56:57], off offset:1024
	s_waitcnt vmcnt(0)
	v_lshlrev_b32_e32 v58, 16, v58
	v_mul_f32_e32 v58, 0xbfb8aa3b, v58
	v_exp_f32_e32 v58, v58
	s_nop 0
	v_add_f32_e32 v58, 1.0, v58
	v_div_scale_f32 v59, s[72:73], v58, v58, 1.0
	v_rcp_f32_e32 v60, v59
	s_nop 0
	v_fma_f32 v61, -v59, v60, 1.0
	v_fmac_f32_e32 v60, v61, v60
	v_div_scale_f32 v61, vcc, 1.0, v58, 1.0
	v_mul_f32_e32 v62, v61, v60
	v_fma_f32 v63, -v59, v62, v61
	v_fmac_f32_e32 v62, v63, v60
	v_fma_f32 v59, -v59, v62, v61
	v_div_fmas_f32 v59, v59, v60, v62
	v_div_fixup_f32 v60, v59, v58, 1.0
	v_add_co_u32_e32 v58, vcc, s88, v4
	s_nop 1
	v_addc_co_u32_e32 v59, vcc, 0, v5, vcc
	global_load_ushort v61, v[58:59], off offset:-4096
	s_waitcnt vmcnt(0)
; __device__ __forceinline__ float bf2f(bfu h) { return __uint_as_float(((unsigned)h) << 16); }
; __device__ __forceinline__ float sigm(float x) { return 1.f / (1.f + __expf(-x)); }
;   __device__ __forceinline__ bfu* glu() const { return (bfu*)(b + L::o_glu); }
; template <int G>
; __device__ __forceinline__ void p2_conformer(const Params& P, const Ptrs<G>& w, int layer, int item, float* cv, int kslot) {
;     ...
;     for (int sr = 0; sr < 62; ++sr) {
;       const int s = t0 - 30 + sr;
;       float h0 = 0.f;
;       if (s >= 0) {
;         const bfu* gp = w.glu() + (seqbase + s) * 1024 + c;
;         h0 = bf2f(gp[0]) * sigm(bf2f(gp[512]));
;       }
; #pragma unroll
;       for (int tr = 0; tr < 32; ++tr) {
;         const int j = sr - tr;
;         if (j >= 0 && j <= 30) a[tr] += wj[j] * h0;
;       }
;     }
	v_lshlrev_b32_e32 v61, 16, v61
	v_mul_f32_e32 v60, v60, v61
	v_fmac_f32_e32 v7, v55, v60
	global_load_ushort v55, v[56:57], off offset:3072
	v_fmac_f32_e32 v22, v6, v60
	global_load_ushort v56, v[56:57], off offset:2048
	v_fmac_f32_e32 v23, v39, v60
	v_fmac_f32_e32 v24, v40, v60
	v_fmac_f32_e32 v25, v41, v60
	v_fmac_f32_e32 v26, v42, v60
	v_fmac_f32_e32 v27, v43, v60
	v_fmac_f32_e32 v28, v44, v60
	v_fmac_f32_e32 v29, v45, v60
	v_fmac_f32_e32 v30, v47, v60
	v_fmac_f32_e32 v31, v46, v60
	v_fmac_f32_e32 v32, v48, v60
	v_fmac_f32_e32 v33, v49, v60
	v_fmac_f32_e32 v34, v50, v60
	v_fmac_f32_e32 v35, v51, v60
	v_fmac_f32_e32 v36, v52, v60
	v_fmac_f32_e32 v37, v53, v60
	v_fmac_f32_e32 v38, v54, v60
	s_waitcnt vmcnt(1)
	v_lshlrev_b32_e32 v55, 16, v55
	v_mul_f32_e32 v55, 0xbfb8aa3b, v55
	v_exp_f32_e32 v55, v55
	s_waitcnt vmcnt(0)
	v_lshlrev_b32_e32 v56, 16, v56
	v_add_f32_e32 v55, 1.0, v55
	v_div_scale_f32 v60, s[72:73], v55, v55, 1.0
	v_rcp_f32_e32 v61, v60
	s_nop 0
	v_fma_f32 v62, -v60, v61, 1.0
	v_fmac_f32_e32 v61, v62, v61
	v_div_scale_f32 v62, vcc, 1.0, v55, 1.0
	v_mul_f32_e32 v63, v62, v61
	v_fma_f32 v64, -v60, v63, v62
	v_fmac_f32_e32 v63, v64, v61
	v_fma_f32 v60, -v60, v63, v62
	v_div_fmas_f32 v60, v60, v61, v63
	v_div_fixup_f32 v55, v60, v55, 1.0
	v_mul_f32_e32 v55, v55, v56
	v_fmac_f32_e32 v7, v54, v55
	global_load_ushort v54, v[58:59], off offset:1024
	v_fmac_f32_e32 v23, v6, v55
	v_fmac_f32_e32 v24, v39, v55
	v_fmac_f32_e32 v25, v40, v55
	v_fmac_f32_e32 v26, v41, v55
	v_fmac_f32_e32 v27, v42, v55
	v_fmac_f32_e32 v28, v43, v55
	v_fmac_f32_e32 v29, v44, v55
	v_fmac_f32_e32 v30, v45, v55
	v_fmac_f32_e32 v31, v47, v55
	v_fmac_f32_e32 v32, v46, v55
	v_fmac_f32_e32 v33, v48, v55
	v_fmac_f32_e32 v34, v49, v55
	v_fmac_f32_e32 v35, v50, v55
	v_fmac_f32_e32 v36, v51, v55
	v_fmac_f32_e32 v37, v52, v55
	v_fmac_f32_e32 v38, v53, v55
	s_waitcnt vmcnt(0)
	v_lshlrev_b32_e32 v54, 16, v54
	v_mul_f32_e32 v54, 0xbfb8aa3b, v54
	v_exp_f32_e32 v54, v54
	s_nop 0
	v_add_f32_e32 v54, 1.0, v54
	v_div_scale_f32 v55, s[72:73], v54, v54, 1.0
	v_rcp_f32_e32 v56, v55
	s_nop 0
	v_fma_f32 v57, -v55, v56, 1.0
	v_fmac_f32_e32 v56, v57, v56
	v_div_scale_f32 v57, vcc, 1.0, v54, 1.0
	v_mul_f32_e32 v60, v57, v56
	v_fma_f32 v61, -v55, v60, v57
	v_fmac_f32_e32 v60, v61, v56
	v_fma_f32 v55, -v55, v60, v57
	v_div_fmas_f32 v55, v55, v56, v60
	v_div_fixup_f32 v54, v55, v54, 1.0
	global_load_ushort v55, v[58:59], off
	s_waitcnt vmcnt(0)
	v_lshlrev_b32_e32 v55, 16, v55
	v_mul_f32_e32 v54, v54, v55
	v_fmac_f32_e32 v7, v53, v54
	global_load_ushort v53, v[58:59], off offset:3072
	v_fmac_f32_e32 v24, v6, v54
	v_fmac_f32_e32 v25, v39, v54
	v_fmac_f32_e32 v26, v40, v54
	v_fmac_f32_e32 v27, v41, v54
	v_fmac_f32_e32 v28, v42, v54
	v_fmac_f32_e32 v29, v43, v54
	v_fmac_f32_e32 v30, v44, v54
	v_fmac_f32_e32 v31, v45, v54
	v_fmac_f32_e32 v32, v47, v54
	v_fmac_f32_e32 v33, v46, v54
	v_fmac_f32_e32 v34, v48, v54
	v_fmac_f32_e32 v35, v49, v54
	v_fmac_f32_e32 v36, v50, v54
	v_fmac_f32_e32 v37, v51, v54
	v_fmac_f32_e32 v38, v52, v54
	s_waitcnt vmcnt(0)
	v_lshlrev_b32_e32 v53, 16, v53
	v_mul_f32_e32 v53, 0xbfb8aa3b, v53
	v_exp_f32_e32 v53, v53
	s_nop 0
	v_add_f32_e32 v53, 1.0, v53
	v_div_scale_f32 v54, s[72:73], v53, v53, 1.0
	v_rcp_f32_e32 v55, v54
	s_mov_b32 s72, 0x9000
	v_fma_f32 v56, -v54, v55, 1.0
	v_fmac_f32_e32 v55, v56, v55
	v_div_scale_f32 v56, vcc, 1.0, v53, 1.0
	v_mul_f32_e32 v57, v56, v55
	v_fma_f32 v60, -v54, v57, v56
	v_fmac_f32_e32 v57, v60, v55
	v_fma_f32 v54, -v54, v57, v56
	v_div_fmas_f32 v54, v54, v55, v57
	v_div_fixup_f32 v53, v54, v53, 1.0
	global_load_ushort v54, v[58:59], off offset:2048
	s_waitcnt vmcnt(0)
	v_lshlrev_b32_e32 v54, 16, v54
	v_mul_f32_e32 v53, v53, v54
	v_fmac_f32_e32 v7, v52, v53
	v_add_co_u32_e32 v52, vcc, s72, v4
	v_fmac_f32_e32 v25, v6, v53
	v_fmac_f32_e32 v26, v39, v53
	v_fmac_f32_e32 v27, v40, v53
	v_fmac_f32_e32 v28, v41, v53
	v_fmac_f32_e32 v29, v42, v53
	v_fmac_f32_e32 v30, v43, v53
	v_fmac_f32_e32 v31, v44, v53
	v_fmac_f32_e32 v32, v45, v53
	v_fmac_f32_e32 v33, v47, v53
	v_fmac_f32_e32 v34, v46, v53
	v_fmac_f32_e32 v35, v48, v53
	v_fmac_f32_e32 v36, v49, v53
	v_fmac_f32_e32 v37, v50, v53
	v_fmac_f32_e32 v38, v51, v53
	v_addc_co_u32_e32 v53, vcc, 0, v5, vcc
	global_load_ushort v54, v[52:53], off offset:1024
	s_waitcnt vmcnt(0)
	v_lshlrev_b32_e32 v54, 16, v54
	v_mul_f32_e32 v54, 0xbfb8aa3b, v54
	v_exp_f32_e32 v54, v54
	s_nop 0
	v_add_f32_e32 v54, 1.0, v54
	v_div_scale_f32 v55, s[72:73], v54, v54, 1.0
	v_rcp_f32_e32 v56, v55
	s_mov_b32 s72, 0xa000
	v_fma_f32 v57, -v55, v56, 1.0
	v_fmac_f32_e32 v56, v57, v56
	v_div_scale_f32 v57, vcc, 1.0, v54, 1.0
	v_mul_f32_e32 v58, v57, v56
	v_fma_f32 v59, -v55, v58, v57
	v_fmac_f32_e32 v58, v59, v56
	v_fma_f32 v55, -v55, v58, v57
	v_div_fmas_f32 v55, v55, v56, v58
	v_div_fixup_f32 v56, v55, v54, 1.0
	v_add_co_u32_e32 v54, vcc, s72, v4
	s_nop 1
	v_addc_co_u32_e32 v55, vcc, 0, v5, vcc
	global_load_ushort v57, v[54:55], off offset:-4096
	s_waitcnt vmcnt(0)
	v_lshlrev_b32_e32 v57, 16, v57
	v_mul_f32_e32 v56, v56, v57
	v_fmac_f32_e32 v7, v51, v56
	global_load_ushort v51, v[52:53], off offset:3072
	v_fmac_f32_e32 v26, v6, v56
	global_load_ushort v52, v[52:53], off offset:2048
	v_fmac_f32_e32 v27, v39, v56
	v_fmac_f32_e32 v28, v40, v56
	v_fmac_f32_e32 v29, v41, v56
	v_fmac_f32_e32 v30, v42, v56
	v_fmac_f32_e32 v31, v43, v56
	v_fmac_f32_e32 v32, v44, v56
	v_fmac_f32_e32 v33, v45, v56
	v_fmac_f32_e32 v34, v47, v56
	v_fmac_f32_e32 v35, v46, v56
	v_fmac_f32_e32 v36, v48, v56
	v_fmac_f32_e32 v37, v49, v56
	v_fmac_f32_e32 v38, v50, v56
	s_waitcnt vmcnt(1)
	v_lshlrev_b32_e32 v51, 16, v51
	v_mul_f32_e32 v51, 0xbfb8aa3b, v51
	v_exp_f32_e32 v51, v51
	s_waitcnt vmcnt(0)
; __device__ __forceinline__ float bf2f(bfu h) { return __uint_as_float(((unsigned)h) << 16); }
; __device__ __forceinline__ float sigm(float x) { return 1.f / (1.f + __expf(-x)); }
;   __device__ __forceinline__ bfu* glu() const { return (bfu*)(b + L::o_glu); }
; template <int G>
; __device__ __forceinline__ void p2_conformer(const Params& P, const Ptrs<G>& w, int layer, int item, float* cv, int kslot) {
;     ...
;     for (int sr = 0; sr < 62; ++sr) {
;       const int s = t0 - 30 + sr;
;       float h0 = 0.f;
;       if (s >= 0) {
;         const bfu* gp = w.glu() + (seqbase + s) * 1024 + c;
;         h0 = bf2f(gp[0]) * sigm(bf2f(gp[512]));
;       }
; #pragma unroll
;       for (int tr = 0; tr < 32; ++tr) {
;         const int j = sr - tr;
;         if (j >= 0 && j <= 30) a[tr] += wj[j] * h0;
;       }
;     }
	v_lshlrev_b32_e32 v52, 16, v52
	v_add_f32_e32 v51, 1.0, v51
	v_div_scale_f32 v56, s[72:73], v51, v51, 1.0
	v_rcp_f32_e32 v57, v56
	s_nop 0
	v_fma_f32 v58, -v56, v57, 1.0
	v_fmac_f32_e32 v57, v58, v57
	v_div_scale_f32 v58, vcc, 1.0, v51, 1.0
	v_mul_f32_e32 v59, v58, v57
	v_fma_f32 v60, -v56, v59, v58
	v_fmac_f32_e32 v59, v60, v57
	v_fma_f32 v56, -v56, v59, v58
	v_div_fmas_f32 v56, v56, v57, v59
	v_div_fixup_f32 v51, v56, v51, 1.0
	v_mul_f32_e32 v51, v51, v52
	v_fmac_f32_e32 v7, v50, v51
	global_load_ushort v50, v[54:55], off offset:1024
	v_fmac_f32_e32 v27, v6, v51
	v_fmac_f32_e32 v28, v39, v51
	v_fmac_f32_e32 v29, v40, v51
	v_fmac_f32_e32 v30, v41, v51
	v_fmac_f32_e32 v31, v42, v51
	v_fmac_f32_e32 v32, v43, v51
	v_fmac_f32_e32 v33, v44, v51
	v_fmac_f32_e32 v34, v45, v51
	v_fmac_f32_e32 v35, v47, v51
	v_fmac_f32_e32 v36, v46, v51
	v_fmac_f32_e32 v37, v48, v51
	v_fmac_f32_e32 v38, v49, v51
	s_waitcnt vmcnt(0)
	v_lshlrev_b32_e32 v50, 16, v50
	v_mul_f32_e32 v50, 0xbfb8aa3b, v50
	v_exp_f32_e32 v50, v50
	s_nop 0
	v_add_f32_e32 v50, 1.0, v50
	v_div_scale_f32 v51, s[72:73], v50, v50, 1.0
	v_rcp_f32_e32 v52, v51
	s_nop 0
	v_fma_f32 v53, -v51, v52, 1.0
	v_fmac_f32_e32 v52, v53, v52
	v_div_scale_f32 v53, vcc, 1.0, v50, 1.0
	v_mul_f32_e32 v56, v53, v52
	v_fma_f32 v57, -v51, v56, v53
	v_fmac_f32_e32 v56, v57, v52
	v_fma_f32 v51, -v51, v56, v53
	v_div_fmas_f32 v51, v51, v52, v56
	v_div_fixup_f32 v50, v51, v50, 1.0
	global_load_ushort v51, v[54:55], off
	s_waitcnt vmcnt(0)
	v_lshlrev_b32_e32 v51, 16, v51
	v_mul_f32_e32 v50, v50, v51
	v_fmac_f32_e32 v7, v49, v50
	global_load_ushort v49, v[54:55], off offset:3072
	v_fmac_f32_e32 v28, v6, v50
	v_fmac_f32_e32 v29, v39, v50
	v_fmac_f32_e32 v30, v40, v50
	v_fmac_f32_e32 v31, v41, v50
	v_fmac_f32_e32 v32, v42, v50
	v_fmac_f32_e32 v33, v43, v50
	v_fmac_f32_e32 v34, v44, v50
	v_fmac_f32_e32 v35, v45, v50
	v_fmac_f32_e32 v36, v47, v50
	v_fmac_f32_e32 v37, v46, v50
	v_fmac_f32_e32 v38, v48, v50
	s_waitcnt vmcnt(0)
	v_lshlrev_b32_e32 v49, 16, v49
	v_mul_f32_e32 v49, 0xbfb8aa3b, v49
	v_exp_f32_e32 v49, v49
	s_nop 0
	v_add_f32_e32 v49, 1.0, v49
	v_div_scale_f32 v50, s[72:73], v49, v49, 1.0
	v_rcp_f32_e32 v51, v50
	s_mov_b32 s72, 0xb000
	v_fma_f32 v52, -v50, v51, 1.0
	v_fmac_f32_e32 v51, v52, v51
	v_div_scale_f32 v52, vcc, 1.0, v49, 1.0
	v_mul_f32_e32 v53, v52, v51
	v_fma_f32 v56, -v50, v53, v52
	v_fmac_f32_e32 v53, v56, v51
	v_fma_f32 v50, -v50, v53, v52
	v_div_fmas_f32 v50, v50, v51, v53
	v_div_fixup_f32 v49, v50, v49, 1.0
	global_load_ushort v50, v[54:55], off offset:2048
	s_waitcnt vmcnt(0)
	v_lshlrev_b32_e32 v50, 16, v50
	v_mul_f32_e32 v49, v49, v50
	v_fmac_f32_e32 v7, v48, v49
	v_add_co_u32_e32 v48, vcc, s72, v4
	v_fmac_f32_e32 v29, v6, v49
	v_fmac_f32_e32 v30, v39, v49
	v_fmac_f32_e32 v31, v40, v49
	v_fmac_f32_e32 v32, v41, v49
	v_fmac_f32_e32 v33, v42, v49
	v_fmac_f32_e32 v34, v43, v49
	v_fmac_f32_e32 v35, v44, v49
	v_fmac_f32_e32 v36, v45, v49
	v_fmac_f32_e32 v37, v47, v49
	v_fmac_f32_e32 v38, v46, v49
	v_addc_co_u32_e32 v49, vcc, 0, v5, vcc
	global_load_ushort v50, v[48:49], off offset:1024
	s_waitcnt vmcnt(0)
	v_lshlrev_b32_e32 v50, 16, v50
	v_mul_f32_e32 v50, 0xbfb8aa3b, v50
	v_exp_f32_e32 v50, v50
	s_nop 0
	v_add_f32_e32 v50, 1.0, v50
	v_div_scale_f32 v51, s[72:73], v50, v50, 1.0
	v_rcp_f32_e32 v52, v51
	s_mov_b32 s72, 0xc000
	v_fma_f32 v53, -v51, v52, 1.0
	v_fmac_f32_e32 v52, v53, v52
	v_div_scale_f32 v53, vcc, 1.0, v50, 1.0
	v_mul_f32_e32 v54, v53, v52
	v_fma_f32 v55, -v51, v54, v53
	v_fmac_f32_e32 v54, v55, v52
	v_fma_f32 v51, -v51, v54, v53
	v_div_fmas_f32 v51, v51, v52, v54
	v_div_fixup_f32 v52, v51, v50, 1.0
	v_add_co_u32_e32 v50, vcc, s72, v4
	s_nop 1
	v_addc_co_u32_e32 v51, vcc, 0, v5, vcc
	global_load_ushort v53, v[50:51], off offset:-4096
	s_waitcnt vmcnt(0)
	v_lshlrev_b32_e32 v53, 16, v53
	v_mul_f32_e32 v52, v52, v53
	v_fmac_f32_e32 v7, v46, v52
	global_load_ushort v46, v[48:49], off offset:3072
	v_fmac_f32_e32 v30, v6, v52
	global_load_ushort v48, v[48:49], off offset:2048
	v_fmac_f32_e32 v31, v39, v52
	v_fmac_f32_e32 v32, v40, v52
	v_fmac_f32_e32 v33, v41, v52
	v_fmac_f32_e32 v34, v42, v52
	v_fmac_f32_e32 v35, v43, v52
	v_fmac_f32_e32 v36, v44, v52
	v_fmac_f32_e32 v37, v45, v52
	v_fmac_f32_e32 v38, v47, v52
	s_waitcnt vmcnt(1)
	v_lshlrev_b32_e32 v46, 16, v46
	v_mul_f32_e32 v46, 0xbfb8aa3b, v46
	v_exp_f32_e32 v46, v46
	s_waitcnt vmcnt(0)
	v_lshlrev_b32_e32 v48, 16, v48
	v_add_f32_e32 v46, 1.0, v46
	v_div_scale_f32 v52, s[72:73], v46, v46, 1.0
	v_rcp_f32_e32 v53, v52
	s_nop 0
	v_fma_f32 v54, -v52, v53, 1.0
	v_fmac_f32_e32 v53, v54, v53
	v_div_scale_f32 v54, vcc, 1.0, v46, 1.0
	v_mul_f32_e32 v55, v54, v53
	v_fma_f32 v56, -v52, v55, v54
	v_fmac_f32_e32 v55, v56, v53
	v_fma_f32 v52, -v52, v55, v54
	v_div_fmas_f32 v52, v52, v53, v55
	v_div_fixup_f32 v46, v52, v46, 1.0
	v_mul_f32_e32 v46, v46, v48
	v_fmac_f32_e32 v31, v6, v46
	v_fmac_f32_e32 v32, v39, v46
	v_fmac_f32_e32 v33, v40, v46
	v_fmac_f32_e32 v34, v41, v46
	v_fmac_f32_e32 v35, v42, v46
	v_fmac_f32_e32 v36, v43, v46
	v_fmac_f32_e32 v37, v44, v46
	v_fmac_f32_e32 v38, v45, v46
	v_fmac_f32_e32 v7, v47, v46
	global_load_ushort v46, v[50:51], off offset:1024
	s_waitcnt vmcnt(0)
	v_lshlrev_b32_e32 v46, 16, v46
	v_mul_f32_e32 v46, 0xbfb8aa3b, v46
	v_exp_f32_e32 v46, v46
	s_nop 0
	v_add_f32_e32 v46, 1.0, v46
	v_div_scale_f32 v47, s[72:73], v46, v46, 1.0
	v_rcp_f32_e32 v48, v47
	s_nop 0
	v_fma_f32 v49, -v47, v48, 1.0
	v_fmac_f32_e32 v48, v49, v48
	v_div_scale_f32 v49, vcc, 1.0, v46, 1.0
	v_mul_f32_e32 v52, v49, v48
	v_fma_f32 v53, -v47, v52, v49
	v_fmac_f32_e32 v52, v53, v48
	v_fma_f32 v47, -v47, v52, v49
	v_div_fmas_f32 v47, v47, v48, v52
	v_div_fixup_f32 v46, v47, v46, 1.0
	global_load_ushort v47, v[50:51], off
	s_waitcnt vmcnt(0)
; __device__ __forceinline__ float bf2f(bfu h) { return __uint_as_float(((unsigned)h) << 16); }
; __device__ __forceinline__ float sigm(float x) { return 1.f / (1.f + __expf(-x)); }
;   __device__ __forceinline__ bfu* glu() const { return (bfu*)(b + L::o_glu); }
; template <int G>
; __device__ __forceinline__ void p2_conformer(const Params& P, const Ptrs<G>& w, int layer, int item, float* cv, int kslot) {
;     ...
;     for (int sr = 0; sr < 62; ++sr) {
;       const int s = t0 - 30 + sr;
;       float h0 = 0.f;
;       if (s >= 0) {
;         const bfu* gp = w.glu() + (seqbase + s) * 1024 + c;
;         h0 = bf2f(gp[0]) * sigm(bf2f(gp[512]));
;       }
; #pragma unroll
;       for (int tr = 0; tr < 32; ++tr) {
;         const int j = sr - tr;
;         if (j >= 0 && j <= 30) a[tr] += wj[j] * h0;
;       }
;     }
	v_lshlrev_b32_e32 v47, 16, v47
	v_mul_f32_e32 v46, v46, v47
	v_fmac_f32_e32 v7, v45, v46
	global_load_ushort v45, v[50:51], off offset:3072
	v_fmac_f32_e32 v32, v6, v46
	v_fmac_f32_e32 v33, v39, v46
	v_fmac_f32_e32 v34, v40, v46
	v_fmac_f32_e32 v35, v41, v46
	v_fmac_f32_e32 v36, v42, v46
	v_fmac_f32_e32 v37, v43, v46
	v_fmac_f32_e32 v38, v44, v46
	s_waitcnt vmcnt(0)
	v_lshlrev_b32_e32 v45, 16, v45
	v_mul_f32_e32 v45, 0xbfb8aa3b, v45
	v_exp_f32_e32 v45, v45
	s_nop 0
	v_add_f32_e32 v45, 1.0, v45
	v_div_scale_f32 v46, s[72:73], v45, v45, 1.0
	v_rcp_f32_e32 v47, v46
	s_mov_b32 s72, 0xd000
	v_fma_f32 v48, -v46, v47, 1.0
	v_fmac_f32_e32 v47, v48, v47
	v_div_scale_f32 v48, vcc, 1.0, v45, 1.0
	v_mul_f32_e32 v49, v48, v47
	v_fma_f32 v52, -v46, v49, v48
	v_fmac_f32_e32 v49, v52, v47
	v_fma_f32 v46, -v46, v49, v48
	v_div_fmas_f32 v46, v46, v47, v49
	v_div_fixup_f32 v45, v46, v45, 1.0
	global_load_ushort v46, v[50:51], off offset:2048
	s_waitcnt vmcnt(0)
	v_lshlrev_b32_e32 v46, 16, v46
	v_mul_f32_e32 v45, v45, v46
	v_fmac_f32_e32 v7, v44, v45
	v_add_co_u32_e32 v44, vcc, s72, v4
	v_fmac_f32_e32 v33, v6, v45
	v_fmac_f32_e32 v34, v39, v45
	v_fmac_f32_e32 v35, v40, v45
	v_fmac_f32_e32 v36, v41, v45
	v_fmac_f32_e32 v37, v42, v45
	v_fmac_f32_e32 v38, v43, v45
	v_addc_co_u32_e32 v45, vcc, 0, v5, vcc
	global_load_ushort v46, v[44:45], off offset:1024
	s_waitcnt vmcnt(0)
	v_lshlrev_b32_e32 v46, 16, v46
	v_mul_f32_e32 v46, 0xbfb8aa3b, v46
	v_exp_f32_e32 v46, v46
	s_nop 0
	v_add_f32_e32 v46, 1.0, v46
	v_div_scale_f32 v47, s[72:73], v46, v46, 1.0
	v_rcp_f32_e32 v48, v47
	s_mov_b32 s72, 0xe000
	v_fma_f32 v49, -v47, v48, 1.0
	v_fmac_f32_e32 v48, v49, v48
	v_div_scale_f32 v49, vcc, 1.0, v46, 1.0
	v_mul_f32_e32 v50, v49, v48
	v_fma_f32 v51, -v47, v50, v49
	v_fmac_f32_e32 v50, v51, v48
	v_fma_f32 v47, -v47, v50, v49
	v_div_fmas_f32 v47, v47, v48, v50
	v_div_fixup_f32 v48, v47, v46, 1.0
	v_add_co_u32_e32 v46, vcc, s72, v4
	s_nop 1
	v_addc_co_u32_e32 v47, vcc, 0, v5, vcc
	global_load_ushort v49, v[46:47], off offset:-4096
	s_waitcnt vmcnt(0)
	v_lshlrev_b32_e32 v49, 16, v49
	v_mul_f32_e32 v48, v48, v49
	v_fmac_f32_e32 v7, v43, v48
	global_load_ushort v43, v[44:45], off offset:3072
	v_fmac_f32_e32 v34, v6, v48
	global_load_ushort v44, v[44:45], off offset:2048
	v_fmac_f32_e32 v35, v39, v48
	v_fmac_f32_e32 v36, v40, v48
	v_fmac_f32_e32 v37, v41, v48
	v_fmac_f32_e32 v38, v42, v48
	s_waitcnt vmcnt(1)
	v_lshlrev_b32_e32 v43, 16, v43
	v_mul_f32_e32 v43, 0xbfb8aa3b, v43
	v_exp_f32_e32 v43, v43
	s_waitcnt vmcnt(0)
	v_lshlrev_b32_e32 v44, 16, v44
	v_add_f32_e32 v43, 1.0, v43
	v_div_scale_f32 v48, s[72:73], v43, v43, 1.0
	v_rcp_f32_e32 v49, v48
	s_nop 0
	v_fma_f32 v50, -v48, v49, 1.0
	v_fmac_f32_e32 v49, v50, v49
	v_div_scale_f32 v50, vcc, 1.0, v43, 1.0
	v_mul_f32_e32 v51, v50, v49
	v_fma_f32 v52, -v48, v51, v50
	v_fmac_f32_e32 v51, v52, v49
	v_fma_f32 v48, -v48, v51, v50
	v_div_fmas_f32 v48, v48, v49, v51
	v_div_fixup_f32 v43, v48, v43, 1.0
	v_mul_f32_e32 v43, v43, v44
	v_fmac_f32_e32 v7, v42, v43
	global_load_ushort v42, v[46:47], off offset:1024
	v_fmac_f32_e32 v35, v6, v43
	v_fmac_f32_e32 v36, v39, v43
	v_fmac_f32_e32 v37, v40, v43
	v_fmac_f32_e32 v38, v41, v43
	s_waitcnt vmcnt(0)
	v_lshlrev_b32_e32 v42, 16, v42
	v_mul_f32_e32 v42, 0xbfb8aa3b, v42
	v_exp_f32_e32 v42, v42
	s_nop 0
	v_add_f32_e32 v42, 1.0, v42
	v_div_scale_f32 v43, s[72:73], v42, v42, 1.0
	v_rcp_f32_e32 v44, v43
	s_nop 0
	v_fma_f32 v45, -v43, v44, 1.0
	v_fmac_f32_e32 v44, v45, v44
	v_div_scale_f32 v45, vcc, 1.0, v42, 1.0
	v_mul_f32_e32 v48, v45, v44
	v_fma_f32 v49, -v43, v48, v45
	v_fmac_f32_e32 v48, v49, v44
	v_fma_f32 v43, -v43, v48, v45
	v_div_fmas_f32 v43, v43, v44, v48
	v_div_fixup_f32 v42, v43, v42, 1.0
	global_load_ushort v43, v[46:47], off
	s_waitcnt vmcnt(0)
	v_lshlrev_b32_e32 v43, 16, v43
	v_mul_f32_e32 v42, v42, v43
	v_fmac_f32_e32 v7, v41, v42
	global_load_ushort v41, v[46:47], off offset:3072
	v_fmac_f32_e32 v36, v6, v42
	v_fmac_f32_e32 v37, v39, v42
	v_fmac_f32_e32 v38, v40, v42
	s_waitcnt vmcnt(0)
	v_lshlrev_b32_e32 v41, 16, v41
	v_mul_f32_e32 v41, 0xbfb8aa3b, v41
	v_exp_f32_e32 v41, v41
	s_nop 0
	v_add_f32_e32 v41, 1.0, v41
	v_div_scale_f32 v42, s[72:73], v41, v41, 1.0
	v_rcp_f32_e32 v43, v42
	s_nop 0
	v_fma_f32 v44, -v42, v43, 1.0
	v_fmac_f32_e32 v43, v44, v43
	v_div_scale_f32 v44, vcc, 1.0, v41, 1.0
	v_mul_f32_e32 v45, v44, v43
	v_fma_f32 v48, -v42, v45, v44
	v_fmac_f32_e32 v45, v48, v43
	v_fma_f32 v42, -v42, v45, v44
	v_div_fmas_f32 v42, v42, v43, v45
	v_div_fixup_f32 v41, v42, v41, 1.0
	global_load_ushort v42, v[46:47], off offset:2048
	v_add_co_u32_e32 v4, vcc, s92, v4
	s_mov_b64 s[92:93], 0
	s_nop 0
	v_addc_co_u32_e32 v5, vcc, 0, v5, vcc
	s_waitcnt vmcnt(0)
	v_lshlrev_b32_e32 v42, 16, v42
	v_mul_f32_e32 v41, v41, v42
	v_fmac_f32_e32 v7, v40, v41
	global_load_ushort v40, v[4:5], off offset:1024
	v_fmac_f32_e32 v37, v6, v41
	v_fmac_f32_e32 v38, v39, v41
	s_waitcnt vmcnt(0)
	v_lshlrev_b32_e32 v40, 16, v40
	v_mul_f32_e32 v40, 0xbfb8aa3b, v40
	v_exp_f32_e32 v40, v40
	s_nop 0
	v_add_f32_e32 v40, 1.0, v40
	v_div_scale_f32 v41, s[72:73], v40, v40, 1.0
	v_rcp_f32_e32 v42, v41
	s_nop 0
	v_fma_f32 v43, -v41, v42, 1.0
	v_fmac_f32_e32 v42, v43, v42
	v_div_scale_f32 v43, vcc, 1.0, v40, 1.0
	v_mul_f32_e32 v44, v43, v42
	v_fma_f32 v45, -v41, v44, v43
	v_fmac_f32_e32 v44, v45, v42
	v_fma_f32 v41, -v41, v44, v43
	v_div_fmas_f32 v41, v41, v42, v44
	v_div_fixup_f32 v40, v41, v40, 1.0
	global_load_ushort v41, v[4:5], off
	s_waitcnt vmcnt(0)
	v_lshlrev_b32_e32 v41, 16, v41
	v_mul_f32_e32 v40, v40, v41
	v_fmac_f32_e32 v7, v39, v40
	global_load_ushort v39, v[4:5], off offset:3072
	v_fmac_f32_e32 v38, v6, v40
	global_load_ushort v4, v[4:5], off offset:2048
	s_waitcnt vmcnt(1)
; __device__ __forceinline__ float bf2f(bfu h) { return __uint_as_float(((unsigned)h) << 16); }
; __device__ __forceinline__ float sigm(float x) { return 1.f / (1.f + __expf(-x)); }
;   __device__ __forceinline__ bfu* glu() const { return (bfu*)(b + L::o_glu); }
; template <int G>
; __device__ __forceinline__ void p2_conformer(const Params& P, const Ptrs<G>& w, int layer, int item, float* cv, int kslot) {
;     ...
;     const int c = tid + 256 * half;
;     float wj[31], a[32];
;     const float* cw = P.conv_dw + (size_t)layer * 31 * 512 + c;
; #pragma unroll
;     for (int j = 0; j < 31; ++j) wj[j] = cw[j * 512];
;     const float b0 = P.conv_dw_bias[layer * 512 + c];
; #pragma unroll
;     for (int t = 0; t < 32; ++t) a[t] = b0;
;     ...
;     for (int sr = 0; sr < 62; ++sr) {
;       const int s = t0 - 30 + sr;
;       float h0 = 0.f;
;       if (s >= 0) {
;         const bfu* gp = w.glu() + (seqbase + s) * 1024 + c;
;         h0 = bf2f(gp[0]) * sigm(bf2f(gp[512]));
;       }
; #pragma unroll
;       for (int tr = 0; tr < 32; ++tr) {
;         const int j = sr - tr;
;         if (j >= 0 && j <= 30) a[tr] += wj[j] * h0;
;       }
;     }
; #pragma unroll
;     for (int tr = 0; tr < 32; ++tr) cv[tr * 512 + c] = a[tr];
	v_lshlrev_b32_e32 v39, 16, v39
	v_mul_f32_e32 v39, 0xbfb8aa3b, v39
	v_exp_f32_e32 v39, v39
	s_waitcnt vmcnt(0)
	v_lshlrev_b32_e32 v4, 16, v4
	v_add_f32_e32 v39, 1.0, v39
	v_div_scale_f32 v40, s[72:73], v39, v39, 1.0
	v_rcp_f32_e32 v41, v40
	s_movk_i32 s72, 0x100
	v_fma_f32 v42, -v40, v41, 1.0
	v_fmac_f32_e32 v41, v42, v41
	v_div_scale_f32 v42, vcc, 1.0, v39, 1.0
	v_mul_f32_e32 v43, v42, v41
	v_fma_f32 v44, -v40, v43, v42
	v_fmac_f32_e32 v43, v44, v41
	v_fma_f32 v40, -v40, v43, v42
	v_div_fmas_f32 v40, v40, v41, v43
	v_div_fixup_f32 v39, v40, v39, 1.0
	v_mul_f32_e32 v4, v39, v4
	s_and_b64 vcc, exec, s[10:11]
	v_fmac_f32_e32 v7, v6, v4
	ds_write2st64_b32 v2, v3, v8 offset1:8
	ds_write2st64_b32 v2, v9, v10 offset0:16 offset1:24
	ds_write2st64_b32 v2, v11, v12 offset0:32 offset1:40
	ds_write2st64_b32 v2, v13, v14 offset0:48 offset1:56
	ds_write2st64_b32 v2, v15, v17 offset0:64 offset1:72
	ds_write2st64_b32 v2, v18, v19 offset0:80 offset1:88
	ds_write2st64_b32 v2, v20, v21 offset0:96 offset1:104
	ds_write2st64_b32 v2, v22, v23 offset0:112 offset1:120
	ds_write2st64_b32 v2, v24, v25 offset0:128 offset1:136
	ds_write2st64_b32 v2, v26, v27 offset0:144 offset1:152
	ds_write2st64_b32 v2, v28, v29 offset0:160 offset1:168
	ds_write2st64_b32 v2, v30, v31 offset0:176 offset1:184
	ds_write2st64_b32 v2, v32, v33 offset0:192 offset1:200
	ds_write2st64_b32 v2, v34, v35 offset0:208 offset1:216
	ds_write2st64_b32 v2, v36, v37 offset0:224 offset1:232
	ds_write2st64_b32 v2, v38, v7 offset0:240 offset1:248
	s_cbranch_vccnz .LBB0_409
.LBB0_349:
	v_add_u32_e32 v2, s72, v16
	v_ashrrev_i32_e32 v3, 31, v2
	v_lshl_add_u64 v[4:5], v[2:3], 2, s[12:13]
	v_add_co_u32_e32 v6, vcc, 0x1000, v4
	global_load_dword v68, v[4:5], off
	global_load_dword v67, v[4:5], off offset:2048
	v_addc_co_u32_e32 v7, vcc, 0, v5, vcc
	global_load_dword v66, v[6:7], off
	global_load_dword v65, v[6:7], off offset:2048
	v_add_co_u32_e32 v6, vcc, 0x2000, v4
	v_readlane_b32 s10, v252, 38
	s_nop 0
	v_addc_co_u32_e32 v7, vcc, 0, v5, vcc
	global_load_dword v64, v[6:7], off
	global_load_dword v63, v[6:7], off offset:2048
	v_add_co_u32_e32 v6, vcc, 0x3000, v4
	v_readlane_b32 s11, v252, 39
	s_nop 0
	v_addc_co_u32_e32 v7, vcc, 0, v5, vcc
	global_load_dword v62, v[6:7], off
	global_load_dword v61, v[6:7], off offset:2048
	v_add_co_u32_e32 v6, vcc, 0x4000, v4
	v_mov_b32_e32 v8, 0
	s_nop 0
	v_addc_co_u32_e32 v7, vcc, 0, v5, vcc
	global_load_dword v60, v[6:7], off
	global_load_dword v59, v[6:7], off offset:2048
	v_add_co_u32_e32 v6, vcc, 0x5000, v4
	s_nop 1
	v_addc_co_u32_e32 v7, vcc, 0, v5, vcc
	global_load_dword v58, v[6:7], off
	global_load_dword v57, v[6:7], off offset:2048
	v_add_co_u32_e32 v6, vcc, s16, v4
	v_readlane_b32 s16, v252, 10
	s_nop 0
	v_addc_co_u32_e32 v7, vcc, 0, v5, vcc
	global_load_dword v56, v[6:7], off
	global_load_dword v55, v[6:7], off offset:2048
	v_add_co_u32_e32 v6, vcc, 0x7000, v4
	v_readlane_b32 s18, v252, 12
	s_nop 0
	v_addc_co_u32_e32 v7, vcc, 0, v5, vcc
	global_load_dword v54, v[6:7], off
	global_load_dword v53, v[6:7], off offset:2048
	v_add_co_u32_e32 v6, vcc, s88, v4
	v_readlane_b32 s19, v252, 13
	s_nop 0
	v_addc_co_u32_e32 v7, vcc, 0, v5, vcc
	global_load_dword v52, v[6:7], off
	global_load_dword v51, v[6:7], off offset:2048
	v_add_co_u32_e32 v6, vcc, 0x9000, v4
	v_readlane_b32 s17, v252, 11
	s_nop 0
	v_addc_co_u32_e32 v7, vcc, 0, v5, vcc
	global_load_dword v50, v[6:7], off
	global_load_dword v49, v[6:7], off offset:2048
	v_add_co_u32_e32 v6, vcc, 0xa000, v4
	v_readlane_b32 s20, v252, 14
	s_nop 0
	v_addc_co_u32_e32 v7, vcc, 0, v5, vcc
	global_load_dword v48, v[6:7], off
	global_load_dword v46, v[6:7], off offset:2048
	v_add_co_u32_e32 v6, vcc, 0xb000, v4
	v_readlane_b32 s21, v252, 15
	s_nop 0
	v_addc_co_u32_e32 v7, vcc, 0, v5, vcc
	global_load_dword v47, v[6:7], off
	global_load_dword v45, v[6:7], off offset:2048
	v_add_co_u32_e32 v6, vcc, 0xc000, v4
	v_readlane_b32 s22, v252, 16
	s_nop 0
	v_addc_co_u32_e32 v7, vcc, 0, v5, vcc
	global_load_dword v44, v[6:7], off
	global_load_dword v43, v[6:7], off offset:2048
	v_add_co_u32_e32 v6, vcc, 0xd000, v4
	v_readlane_b32 s23, v252, 17
	s_nop 0
	v_addc_co_u32_e32 v7, vcc, 0, v5, vcc
	global_load_dword v42, v[6:7], off
	global_load_dword v41, v[6:7], off offset:2048
	v_add_co_u32_e32 v6, vcc, 0xe000, v4
	v_readlane_b32 s24, v252, 18
	s_nop 0
	v_addc_co_u32_e32 v7, vcc, 0, v5, vcc
	v_add_co_u32_e32 v4, vcc, 0xf000, v4
	global_load_dword v40, v[6:7], off
	global_load_dword v39, v[6:7], off offset:2048
	v_addc_co_u32_e32 v5, vcc, 0, v5, vcc
	global_load_dword v6, v[4:5], off
	v_add_u32_e32 v4, s94, v2
	v_ashrrev_i32_e32 v5, 31, v4
	v_lshl_add_u64 v[4:5], v[4:5], 2, s[18:19]
	global_load_dword v7, v[4:5], off
	v_lshl_add_u64 v[4:5], v[2:3], 1, s[10:11]
	s_and_b64 vcc, exec, s[14:15]
	s_cbranch_vccz .Lcpf_skip
; __device__ __forceinline__ float bf2f(bfu h) { return __uint_as_float(((unsigned)h) << 16); }
; __device__ __forceinline__ float sigm(float x) { return 1.f / (1.f + __expf(-x)); }
;   __device__ __forceinline__ bfu* glu() const { return (bfu*)(b + L::o_glu); }
; template <int G>
; __device__ __forceinline__ void p2_conformer(const Params& P, const Ptrs<G>& w, int layer, int item, float* cv, int kslot) {
;     ...
;     const int c = tid + 256 * half;
;     float wj[31], a[32];
;     const float* cw = P.conv_dw + (size_t)layer * 31 * 512 + c;
; #pragma unroll
;     for (int j = 0; j < 31; ++j) wj[j] = cw[j * 512];
;     const float b0 = P.conv_dw_bias[layer * 512 + c];
; #pragma unroll
;     for (int t = 0; t < 32; ++t) a[t] = b0;
; #pragma unroll
;     for (int sr = 0; sr < 62; ++sr) {
;       const int s = t0 - 30 + sr;
;       float h0 = 0.f;
;       if (s >= 0) {
;         const bfu* gp = w.glu() + (seqbase + s) * 1024 + c;
;         h0 = bf2f(gp[0]) * sigm(bf2f(gp[512]));
;       }
; #pragma unroll
;       for (int tr = 0; tr < 32; ++tr) {
;         const int j = sr - tr;
;         if (j >= 0 && j <= 30) a[tr] += wj[j] * h0;
;       }
;     }
	v_readlane_b32 s16, v254, 53
	v_readlane_b32 s17, v254, 54
	s_nop 1
	v_lshl_add_u64 v[10:11], v[4:5], 0, s[16:17]
	s_mov_b64 s[16:17], 0x1000
	v_lshl_add_u64 v[10:11], v[10:11], 0, s[16:17]
	s_mov_b64 s[16:17], 0x2000
	global_load_ushort v8, v[10:11], off offset:-4096
	global_load_ushort v8, v[10:11], off offset:-3072
	global_load_ushort v8, v[10:11], off offset:-2048
	global_load_ushort v8, v[10:11], off offset:-1024
	global_load_ushort v8, v[10:11], off
	global_load_ushort v8, v[10:11], off offset:1024
	global_load_ushort v8, v[10:11], off offset:2048
	global_load_ushort v8, v[10:11], off offset:3072
	v_lshl_add_u64 v[10:11], v[10:11], 0, s[16:17]
	global_load_ushort v8, v[10:11], off offset:-4096
	global_load_ushort v8, v[10:11], off offset:-3072
	global_load_ushort v8, v[10:11], off offset:-2048
	global_load_ushort v8, v[10:11], off offset:-1024
	global_load_ushort v8, v[10:11], off
	global_load_ushort v8, v[10:11], off offset:1024
	global_load_ushort v8, v[10:11], off offset:2048
	global_load_ushort v8, v[10:11], off offset:3072
	v_lshl_add_u64 v[10:11], v[10:11], 0, s[16:17]
	global_load_ushort v8, v[10:11], off offset:-4096
	global_load_ushort v8, v[10:11], off offset:-3072
	global_load_ushort v8, v[10:11], off offset:-2048
	global_load_ushort v8, v[10:11], off offset:-1024
	global_load_ushort v8, v[10:11], off
	global_load_ushort v8, v[10:11], off offset:1024
	global_load_ushort v8, v[10:11], off offset:2048
	global_load_ushort v8, v[10:11], off offset:3072
	v_lshl_add_u64 v[10:11], v[10:11], 0, s[16:17]
	global_load_ushort v8, v[10:11], off offset:-4096
	global_load_ushort v8, v[10:11], off offset:-3072
	global_load_ushort v8, v[10:11], off offset:-2048
	global_load_ushort v8, v[10:11], off offset:-1024
	global_load_ushort v8, v[10:11], off
	global_load_ushort v8, v[10:11], off offset:1024
	global_load_ushort v8, v[10:11], off offset:2048
	global_load_ushort v8, v[10:11], off offset:3072
	v_lshl_add_u64 v[10:11], v[10:11], 0, s[16:17]
	global_load_ushort v8, v[10:11], off offset:-4096
	global_load_ushort v8, v[10:11], off offset:-3072
	global_load_ushort v8, v[10:11], off offset:-2048
	global_load_ushort v8, v[10:11], off offset:-1024
	global_load_ushort v8, v[10:11], off
	global_load_ushort v8, v[10:11], off offset:1024
	global_load_ushort v8, v[10:11], off offset:2048
	global_load_ushort v8, v[10:11], off offset:3072
	v_lshl_add_u64 v[10:11], v[10:11], 0, s[16:17]
	global_load_ushort v8, v[10:11], off offset:-4096
	global_load_ushort v8, v[10:11], off offset:-3072
	global_load_ushort v8, v[10:11], off offset:-2048
	global_load_ushort v8, v[10:11], off offset:-1024
	global_load_ushort v8, v[10:11], off
	global_load_ushort v8, v[10:11], off offset:1024
	global_load_ushort v8, v[10:11], off offset:2048
	global_load_ushort v8, v[10:11], off offset:3072
	v_lshl_add_u64 v[10:11], v[10:11], 0, s[16:17]
	global_load_ushort v8, v[10:11], off offset:-4096
	global_load_ushort v8, v[10:11], off offset:-3072
	global_load_ushort v8, v[10:11], off offset:-2048
	global_load_ushort v8, v[10:11], off offset:-1024
	global_load_ushort v8, v[10:11], off
	global_load_ushort v8, v[10:11], off offset:1024
	global_load_ushort v8, v[10:11], off offset:2048
	global_load_ushort v8, v[10:11], off offset:3072
	v_lshl_add_u64 v[10:11], v[10:11], 0, s[16:17]
	global_load_ushort v8, v[10:11], off offset:-4096
	global_load_ushort v8, v[10:11], off offset:-3072
	global_load_ushort v8, v[10:11], off offset:-2048
	global_load_ushort v8, v[10:11], off offset:-1024
.Lcpf_skip:
	v_cndmask_b32_e64 v3, 0, 1, s[14:15]
	v_cmp_ne_u32_e64 s[10:11], 1, v3
	s_andn2_b64 vcc, exec, s[14:15]
	v_mov_b32_e32 v3, 0
	v_readlane_b32 s25, v252, 19
	v_readlane_b32 s26, v252, 20
	v_readlane_b32 s27, v252, 21
	v_readlane_b32 s28, v252, 22
	v_readlane_b32 s29, v252, 23
	v_readlane_b32 s30, v252, 24
	v_readlane_b32 s31, v252, 25
	s_cbranch_vccnz .LBB0_351
	v_readlane_b32 s16, v254, 53
	v_readlane_b32 s17, v254, 54
	s_nop 1
	v_lshl_add_u64 v[10:11], v[4:5], 0, s[16:17]
	global_load_ushort v3, v[10:11], off offset:1024
	global_load_ushort v9, v[10:11], off
	s_waitcnt vmcnt(1)
	v_lshlrev_b32_e32 v3, 16, v3
	v_mul_f32_e32 v3, 0xbfb8aa3b, v3
	v_exp_f32_e32 v3, v3
	s_waitcnt vmcnt(0)
	v_lshlrev_b32_e32 v9, 16, v9
	v_add_f32_e32 v3, 1.0, v3
	v_div_scale_f32 v10, s[72:73], v3, v3, 1.0
	v_rcp_f32_e32 v11, v10
	v_div_scale_f32 v12, vcc, 1.0, v3, 1.0
	v_fma_f32 v13, -v10, v11, 1.0
	v_fmac_f32_e32 v11, v13, v11
	v_mul_f32_e32 v13, v12, v11
	v_fma_f32 v14, -v10, v13, v12
	v_fmac_f32_e32 v13, v14, v11
	v_fma_f32 v10, -v10, v13, v12
	v_div_fmas_f32 v10, v10, v11, v13
	v_div_fixup_f32 v3, v10, v3, 1.0
	v_mul_f32_e32 v3, v3, v9
